# hand-written RoPE epilogue for the layer-0 in-projection: cos/sin rows of three row groups in flight (counted waits, no store drain), lane^32 partner via permlane32 swap instead of ds_bpermute
# speedup vs baseline: 1.0219x; 1.0038x over previous
; __device__ __forceinline__ unsigned cvt_pk_bf16(float lo, float hi) { f32x2_t v = {lo, hi}; bf16x2_t b = __builtin_convertvector(v, bf16x2_t); return __builtin_bit_cast(unsigned, b); }
;     __device__ __forceinline__ void operator()(const f32x4 (&acc)[2][2][4][2], const Unit& u, int wr, int wc, int fr, int fq) const {
;         const int row0 = u.pm * BM + wr * 64 + fr; const int col0 = u.pn * BM + wc * 32 + 8 * fq;
;         const int axis = wc & 1; const float sgn = (fq & 2) ? 1.0f : -1.0f; const int i0 = 8 * (fq & 1);
; #pragma unroll
;         for (int ai = 0; ai < 2; ++ai)
; #pragma unroll
;             for (int m = 0; m < 4; ++m) { const int row = row0 + ai * HALF + m * 16; bf16_t* rowp = O + (size_t)row * ldc + col0;
;                 const int s = row % seq; const int pos = axis ? (s & 63) : (s >> 6);
;                 const f32x4* rp = (const f32x4*)(rope + ((size_t)pos * 16 + i0) * 2);
; #pragma unroll
;                 for (int bj = 0; bj < 2; ++bj) { f32x4 v0 = acc[ai][bj][m][0], v1 = acc[ai][bj][m][1];
;                     const bool do_rope = (u.pn < 2) || (u.pn == 2 && bj == 0);
;                     if (do_rope) {
;                         const f32x4 cs0 = rp[0], cs1 = rp[1], cs2 = rp[2], cs3 = rp[3];
;                         f32x4 p0, p1;
; #pragma unroll
;                         for (int j = 0; j < 4; ++j) { p0[j] = __shfl_xor(v0[j], 32); p1[j] = __shfl_xor(v1[j], 32); }
;                         const float sc = (u.pn < 2) ? 0.125f * 1.4426950408889634f : 1.0f;
;                         v0[0] = (v0[0] * cs0[0] + sgn * p0[0] * cs0[1]) * sc; v0[1] = (v0[1] * cs0[2] + sgn * p0[1] * cs0[3]) * sc;
;                         v0[2] = (v0[2] * cs1[0] + sgn * p0[2] * cs1[1]) * sc; v0[3] = (v0[3] * cs1[2] + sgn * p0[3] * cs1[3]) * sc;
;                         v1[0] = (v1[0] * cs2[0] + sgn * p1[0] * cs2[1]) * sc; v1[1] = (v1[1] * cs2[2] + sgn * p1[1] * cs2[3]) * sc;
;                         v1[2] = (v1[2] * cs3[0] + sgn * p1[2] * cs3[1]) * sc; v1[3] = (v1[3] * cs3[2] + sgn * p1[3] * cs3[3]) * sc;
;                     }
;                     u32x4 w; w.x = cvt_pk_bf16(v0[0], v0[1]); w.y = cvt_pk_bf16(v0[2], v0[3]); w.z = cvt_pk_bf16(v1[0], v1[1]); w.w = cvt_pk_bf16(v1[2], v1[3]);
;                     *(u32x4*)(rowp + bj * HALF) = w; } }
.LBB0_341:
	v_lshl_add_u32 v167, s4, 8, v160
	v_mul_u32_u24_e32 v150, 0xe00, v167
	s_lshl_b32 s56, s40, 9
	v_lshl_add_u32 v150, v162, 1, v150
	v_add_u32_e32 v150, s56, v150
	s_cmp_lt_u32 s40, 2
	s_cbranch_scc1 .Lrope_q
	s_cmp_eq_u32 s40, 2
	s_cbranch_scc1 .Lrope_k
	v_mov_b32_e32 v151, v150
	v_cvt_pk_bf16_f32 v124, v124, v125
	v_cvt_pk_bf16_f32 v125, v126, v127
	v_cvt_pk_bf16_f32 v126, v120, v121
	v_cvt_pk_bf16_f32 v127, v122, v123
	global_store_dwordx4 v151, v[124:127], s[48:49]
	v_cvt_pk_bf16_f32 v116, v116, v117
	v_cvt_pk_bf16_f32 v117, v118, v119
	v_cvt_pk_bf16_f32 v118, v112, v113
	v_cvt_pk_bf16_f32 v119, v114, v115
	global_store_dwordx4 v151, v[116:119], s[48:49] offset:256
	v_add_u32_e32 v151, 0xe000, v150
	v_cvt_pk_bf16_f32 v108, v108, v109
	v_cvt_pk_bf16_f32 v109, v110, v111
	v_cvt_pk_bf16_f32 v110, v104, v105
	v_cvt_pk_bf16_f32 v111, v106, v107
	global_store_dwordx4 v151, v[108:111], s[48:49]
	v_cvt_pk_bf16_f32 v100, v100, v101
	v_cvt_pk_bf16_f32 v101, v102, v103
	v_cvt_pk_bf16_f32 v102, v96, v97
	v_cvt_pk_bf16_f32 v103, v98, v99
	global_store_dwordx4 v151, v[100:103], s[48:49] offset:256
	v_add_u32_e32 v151, 0x1c000, v150
	v_cvt_pk_bf16_f32 v92, v92, v93
	v_cvt_pk_bf16_f32 v93, v94, v95
	v_cvt_pk_bf16_f32 v94, v88, v89
	v_cvt_pk_bf16_f32 v95, v90, v91
	global_store_dwordx4 v151, v[92:95], s[48:49]
	v_cvt_pk_bf16_f32 v84, v84, v85
	v_cvt_pk_bf16_f32 v85, v86, v87
	v_cvt_pk_bf16_f32 v86, v80, v81
	v_cvt_pk_bf16_f32 v87, v82, v83
	global_store_dwordx4 v151, v[84:87], s[48:49] offset:256
	v_add_u32_e32 v151, 0x2a000, v150
	v_cvt_pk_bf16_f32 v76, v76, v77
	v_cvt_pk_bf16_f32 v77, v78, v79
	v_cvt_pk_bf16_f32 v78, v72, v73
	v_cvt_pk_bf16_f32 v79, v74, v75
	global_store_dwordx4 v151, v[76:79], s[48:49]
	v_cvt_pk_bf16_f32 v68, v68, v69
	v_cvt_pk_bf16_f32 v69, v70, v71
	v_cvt_pk_bf16_f32 v70, v64, v65
	v_cvt_pk_bf16_f32 v71, v66, v67
	global_store_dwordx4 v151, v[68:71], s[48:49] offset:256
	v_add_u32_e32 v151, 0x70000, v150
	v_cvt_pk_bf16_f32 v60, v60, v61
	v_cvt_pk_bf16_f32 v61, v62, v63
	v_cvt_pk_bf16_f32 v62, v56, v57
	v_cvt_pk_bf16_f32 v63, v58, v59
	global_store_dwordx4 v151, v[60:63], s[48:49]
	v_cvt_pk_bf16_f32 v52, v52, v53
	v_cvt_pk_bf16_f32 v53, v54, v55
	v_cvt_pk_bf16_f32 v54, v48, v49
	v_cvt_pk_bf16_f32 v55, v50, v51
	global_store_dwordx4 v151, v[52:55], s[48:49] offset:256
	v_add_u32_e32 v151, 0x7e000, v150
	v_cvt_pk_bf16_f32 v44, v44, v45
	v_cvt_pk_bf16_f32 v45, v46, v47
	v_cvt_pk_bf16_f32 v46, v40, v41
	v_cvt_pk_bf16_f32 v47, v42, v43
	global_store_dwordx4 v151, v[44:47], s[48:49]
	v_cvt_pk_bf16_f32 v36, v36, v37
	v_cvt_pk_bf16_f32 v37, v38, v39
	v_cvt_pk_bf16_f32 v38, v32, v33
	v_cvt_pk_bf16_f32 v39, v34, v35
	global_store_dwordx4 v151, v[36:39], s[48:49] offset:256
	v_add_u32_e32 v151, 0x8c000, v150
	v_cvt_pk_bf16_f32 v28, v28, v29
	v_cvt_pk_bf16_f32 v29, v30, v31
	v_cvt_pk_bf16_f32 v30, v24, v25
	v_cvt_pk_bf16_f32 v31, v26, v27
	global_store_dwordx4 v151, v[28:31], s[48:49]
	v_cvt_pk_bf16_f32 v20, v20, v21
	v_cvt_pk_bf16_f32 v21, v22, v23
	v_cvt_pk_bf16_f32 v22, v16, v17
	v_cvt_pk_bf16_f32 v23, v18, v19
	global_store_dwordx4 v151, v[20:23], s[48:49] offset:256
	v_add_u32_e32 v151, 0x9a000, v150
	v_cvt_pk_bf16_f32 v12, v12, v13
	v_cvt_pk_bf16_f32 v13, v14, v15
	v_cvt_pk_bf16_f32 v14, v8, v9
	v_cvt_pk_bf16_f32 v15, v10, v11
	global_store_dwordx4 v151, v[12:15], s[48:49]
	v_cvt_pk_bf16_f32 v4, v4, v5
	v_cvt_pk_bf16_f32 v5, v6, v7
	v_cvt_pk_bf16_f32 v6, v0, v1
	v_cvt_pk_bf16_f32 v7, v2, v3
	global_store_dwordx4 v151, v[4:7], s[48:49] offset:256
	s_branch .Lrope_done
.Lrope_q:
	v_and_b32_e32 v236, 8, v162
	v_lshlrev_b32_e32 v236, 3, v236
	s_add_u32 s60, s50, 0x130000
	s_addc_u32 s61, s51, 0
	s_mov_b32 s58, -1
	s_mov_b32 s59, 0
	v_mov_b32_e32 v237, v167
	v_bfe_u32 v151, v237, 6, 8
	v_and_b32_e32 v237, 63, v237
	v_cndmask_b32_e64 v237, v237, v151, s[8:9]
	v_lshl_add_u32 v149, v237, 7, v236
	global_load_dwordx4 v[168:171], v149, s[60:61]
	global_load_dwordx4 v[172:175], v149, s[60:61] offset:16
	global_load_dwordx4 v[176:179], v149, s[60:61] offset:32
	global_load_dwordx4 v[180:183], v149, s[60:61] offset:48
	v_add_u32_e32 v237, 16, v167
	v_bfe_u32 v151, v237, 6, 8
	v_and_b32_e32 v237, 63, v237
	v_cndmask_b32_e64 v237, v237, v151, s[8:9]
	v_lshl_add_u32 v149, v237, 7, v236
	global_load_dwordx4 v[184:187], v149, s[60:61]
	global_load_dwordx4 v[188:191], v149, s[60:61] offset:16
	global_load_dwordx4 v[192:195], v149, s[60:61] offset:32
	global_load_dwordx4 v[196:199], v149, s[60:61] offset:48
	v_add_u32_e32 v237, 32, v167
	v_bfe_u32 v151, v237, 6, 8
	v_and_b32_e32 v237, 63, v237
	v_cndmask_b32_e64 v237, v237, v151, s[8:9]
	v_lshl_add_u32 v149, v237, 7, v236
	global_load_dwordx4 v[208:211], v149, s[60:61]
	global_load_dwordx4 v[212:215], v149, s[60:61] offset:16
	global_load_dwordx4 v[216:219], v149, s[60:61] offset:32
	global_load_dwordx4 v[220:223], v149, s[60:61] offset:48
	s_waitcnt vmcnt(8)
; __device__ __forceinline__ unsigned cvt_pk_bf16(float lo, float hi) { f32x2_t v = {lo, hi}; bf16x2_t b = __builtin_convertvector(v, bf16x2_t); return __builtin_bit_cast(unsigned, b); }
;     __device__ __forceinline__ void operator()(const f32x4 (&acc)[2][2][4][2], const Unit& u, int wr, int wc, int fr, int fq) const {
;     ...
;             for (int m = 0; m < 4; ++m) { const int row = row0 + ai * HALF + m * 16; bf16_t* rowp = O + (size_t)row * ldc + col0;
;                 const int s = row % seq; const int pos = axis ? (s & 63) : (s >> 6);
;                 const f32x4* rp = (const f32x4*)(rope + ((size_t)pos * 16 + i0) * 2);
; #pragma unroll
;                 for (int bj = 0; bj < 2; ++bj) { f32x4 v0 = acc[ai][bj][m][0], v1 = acc[ai][bj][m][1];
;                     const bool do_rope = (u.pn < 2) || (u.pn == 2 && bj == 0);
;                     if (do_rope) {
;                         const f32x4 cs0 = rp[0], cs1 = rp[1], cs2 = rp[2], cs3 = rp[3];
;                         f32x4 p0, p1;
; #pragma unroll
;                         for (int j = 0; j < 4; ++j) { p0[j] = __shfl_xor(v0[j], 32); p1[j] = __shfl_xor(v1[j], 32); }
;                         const float sc = (u.pn < 2) ? 0.125f * 1.4426950408889634f : 1.0f;
;                         v0[0] = (v0[0] * cs0[0] + sgn * p0[0] * cs0[1]) * sc; v0[1] = (v0[1] * cs0[2] + sgn * p0[1] * cs0[3]) * sc;
;                         v0[2] = (v0[2] * cs1[0] + sgn * p0[2] * cs1[1]) * sc; v0[3] = (v0[3] * cs1[2] + sgn * p0[3] * cs1[3]) * sc;
;                         v1[0] = (v1[0] * cs2[0] + sgn * p1[0] * cs2[1]) * sc; v1[1] = (v1[1] * cs2[2] + sgn * p1[1] * cs2[3]) * sc;
;                         v1[2] = (v1[2] * cs3[0] + sgn * p1[2] * cs3[1]) * sc; v1[3] = (v1[3] * cs3[2] + sgn * p1[3] * cs3[3]) * sc;
;                     }
;                     u32x4 w; w.x = cvt_pk_bf16(v0[0], v0[1]); w.y = cvt_pk_bf16(v0[2], v0[3]); w.z = cvt_pk_bf16(v1[0], v1[1]); w.w = cvt_pk_bf16(v1[2], v1[3]);
;                     *(u32x4*)(rowp + bj * HALF) = w; } }
	v_cndmask_b32_e64 v224, v169, v168, s[58:59]
	v_cndmask_b32_e64 v200, v168, -v169, s[58:59]
	v_cndmask_b32_e64 v225, v171, v170, s[58:59]
	v_cndmask_b32_e64 v201, v170, -v171, s[58:59]
	v_cndmask_b32_e64 v226, v173, v172, s[58:59]
	v_cndmask_b32_e64 v202, v172, -v173, s[58:59]
	v_cndmask_b32_e64 v227, v175, v174, s[58:59]
	v_cndmask_b32_e64 v203, v174, -v175, s[58:59]
	v_cndmask_b32_e64 v228, v177, v176, s[58:59]
	v_cndmask_b32_e64 v232, v176, -v177, s[58:59]
	v_cndmask_b32_e64 v229, v179, v178, s[58:59]
	v_cndmask_b32_e64 v233, v178, -v179, s[58:59]
	v_cndmask_b32_e64 v230, v181, v180, s[58:59]
	v_cndmask_b32_e64 v234, v180, -v181, s[58:59]
	v_cndmask_b32_e64 v231, v183, v182, s[58:59]
	v_cndmask_b32_e64 v235, v182, -v183, s[58:59]
	v_add_u32_e32 v237, 48, v167
	v_bfe_u32 v151, v237, 6, 8
	v_and_b32_e32 v237, 63, v237
	v_cndmask_b32_e64 v237, v237, v151, s[8:9]
	v_lshl_add_u32 v149, v237, 7, v236
	global_load_dwordx4 v[168:171], v149, s[60:61]
	global_load_dwordx4 v[172:175], v149, s[60:61] offset:16
	global_load_dwordx4 v[176:179], v149, s[60:61] offset:32
	global_load_dwordx4 v[180:183], v149, s[60:61] offset:48
	v_mov_b32_e32 v146, v124
	v_mov_b32_e32 v147, v125
	v_mov_b32_e32 v148, v126
	v_mov_b32_e32 v149, v127
	v_permlane32_swap_b32_e32 v124, v146
	v_permlane32_swap_b32_e32 v125, v147
	v_permlane32_swap_b32_e32 v126, v148
	v_permlane32_swap_b32_e32 v127, v149
	v_pk_mul_f32 v[146:147], v[146:147], v[200:201]
	v_pk_mul_f32 v[148:149], v[148:149], v[202:203]
	v_pk_fma_f32 v[124:125], v[124:125], v[224:225], v[146:147]
	v_pk_fma_f32 v[126:127], v[126:127], v[226:227], v[148:149]
	v_pk_mul_f32 v[124:125], v[124:125], s[24:25] op_sel_hi:[1,0]
	v_pk_mul_f32 v[126:127], v[126:127], s[24:25] op_sel_hi:[1,0]
	v_mov_b32_e32 v146, v120
	v_mov_b32_e32 v147, v121
	v_mov_b32_e32 v148, v122
	v_mov_b32_e32 v149, v123
	v_permlane32_swap_b32_e32 v120, v146
	v_permlane32_swap_b32_e32 v121, v147
	v_permlane32_swap_b32_e32 v122, v148
	v_permlane32_swap_b32_e32 v123, v149
	v_pk_mul_f32 v[146:147], v[146:147], v[232:233]
	v_pk_mul_f32 v[148:149], v[148:149], v[234:235]
	v_pk_fma_f32 v[120:121], v[120:121], v[228:229], v[146:147]
	v_pk_fma_f32 v[122:123], v[122:123], v[230:231], v[148:149]
	v_pk_mul_f32 v[120:121], v[120:121], s[24:25] op_sel_hi:[1,0]
	v_pk_mul_f32 v[122:123], v[122:123], s[24:25] op_sel_hi:[1,0]
	v_mov_b32_e32 v146, v116
	v_mov_b32_e32 v147, v117
	v_mov_b32_e32 v148, v118
	v_mov_b32_e32 v149, v119
	v_permlane32_swap_b32_e32 v116, v146
	v_permlane32_swap_b32_e32 v117, v147
	v_permlane32_swap_b32_e32 v118, v148
	v_permlane32_swap_b32_e32 v119, v149
	v_pk_mul_f32 v[146:147], v[146:147], v[200:201]
	v_pk_mul_f32 v[148:149], v[148:149], v[202:203]
	v_pk_fma_f32 v[116:117], v[116:117], v[224:225], v[146:147]
	v_pk_fma_f32 v[118:119], v[118:119], v[226:227], v[148:149]
	v_pk_mul_f32 v[116:117], v[116:117], s[24:25] op_sel_hi:[1,0]
	v_pk_mul_f32 v[118:119], v[118:119], s[24:25] op_sel_hi:[1,0]
	v_mov_b32_e32 v146, v112
	v_mov_b32_e32 v147, v113
	v_mov_b32_e32 v148, v114
	v_mov_b32_e32 v149, v115
	v_permlane32_swap_b32_e32 v112, v146
	v_permlane32_swap_b32_e32 v113, v147
	v_permlane32_swap_b32_e32 v114, v148
	v_permlane32_swap_b32_e32 v115, v149
	v_pk_mul_f32 v[146:147], v[146:147], v[232:233]
	v_pk_mul_f32 v[148:149], v[148:149], v[234:235]
	v_pk_fma_f32 v[112:113], v[112:113], v[228:229], v[146:147]
	v_pk_fma_f32 v[114:115], v[114:115], v[230:231], v[148:149]
	v_pk_mul_f32 v[112:113], v[112:113], s[24:25] op_sel_hi:[1,0]
	v_pk_mul_f32 v[114:115], v[114:115], s[24:25] op_sel_hi:[1,0]
	v_mov_b32_e32 v151, v150
	v_cvt_pk_bf16_f32 v124, v124, v125
	v_cvt_pk_bf16_f32 v125, v126, v127
	v_cvt_pk_bf16_f32 v126, v120, v121
	v_cvt_pk_bf16_f32 v127, v122, v123
	global_store_dwordx4 v151, v[124:127], s[48:49]
	v_cvt_pk_bf16_f32 v116, v116, v117
	v_cvt_pk_bf16_f32 v117, v118, v119
	v_cvt_pk_bf16_f32 v118, v112, v113
	v_cvt_pk_bf16_f32 v119, v114, v115
	global_store_dwordx4 v151, v[116:119], s[48:49] offset:256
	s_waitcnt vmcnt(10)
	v_cndmask_b32_e64 v224, v185, v184, s[58:59]
	v_cndmask_b32_e64 v200, v184, -v185, s[58:59]
	v_cndmask_b32_e64 v225, v187, v186, s[58:59]
	v_cndmask_b32_e64 v201, v186, -v187, s[58:59]
	v_cndmask_b32_e64 v226, v189, v188, s[58:59]
	v_cndmask_b32_e64 v202, v188, -v189, s[58:59]
	v_cndmask_b32_e64 v227, v191, v190, s[58:59]
	v_cndmask_b32_e64 v203, v190, -v191, s[58:59]
	v_cndmask_b32_e64 v228, v193, v192, s[58:59]
	v_cndmask_b32_e64 v232, v192, -v193, s[58:59]
	v_cndmask_b32_e64 v229, v195, v194, s[58:59]
	v_cndmask_b32_e64 v233, v194, -v195, s[58:59]
	v_cndmask_b32_e64 v230, v197, v196, s[58:59]
	v_cndmask_b32_e64 v234, v196, -v197, s[58:59]
	v_cndmask_b32_e64 v231, v199, v198, s[58:59]
	v_cndmask_b32_e64 v235, v198, -v199, s[58:59]
	v_add_u32_e32 v237, 128, v167
	v_bfe_u32 v151, v237, 6, 8
	v_and_b32_e32 v237, 63, v237
	v_cndmask_b32_e64 v237, v237, v151, s[8:9]
	v_lshl_add_u32 v149, v237, 7, v236
	global_load_dwordx4 v[184:187], v149, s[60:61]
	global_load_dwordx4 v[188:191], v149, s[60:61] offset:16
	global_load_dwordx4 v[192:195], v149, s[60:61] offset:32
	global_load_dwordx4 v[196:199], v149, s[60:61] offset:48
	v_mov_b32_e32 v146, v108
	v_mov_b32_e32 v147, v109
	v_mov_b32_e32 v148, v110
	v_mov_b32_e32 v149, v111
	v_permlane32_swap_b32_e32 v108, v146
	v_permlane32_swap_b32_e32 v109, v147
	v_permlane32_swap_b32_e32 v110, v148
	v_permlane32_swap_b32_e32 v111, v149
	v_pk_mul_f32 v[146:147], v[146:147], v[200:201]
	v_pk_mul_f32 v[148:149], v[148:149], v[202:203]
	v_pk_fma_f32 v[108:109], v[108:109], v[224:225], v[146:147]
	v_pk_fma_f32 v[110:111], v[110:111], v[226:227], v[148:149]
	v_pk_mul_f32 v[108:109], v[108:109], s[24:25] op_sel_hi:[1,0]
; __device__ __forceinline__ unsigned cvt_pk_bf16(float lo, float hi) { f32x2_t v = {lo, hi}; bf16x2_t b = __builtin_convertvector(v, bf16x2_t); return __builtin_bit_cast(unsigned, b); }
;     __device__ __forceinline__ void operator()(const f32x4 (&acc)[2][2][4][2], const Unit& u, int wr, int wc, int fr, int fq) const {
;     ...
;             for (int m = 0; m < 4; ++m) { const int row = row0 + ai * HALF + m * 16; bf16_t* rowp = O + (size_t)row * ldc + col0;
;                 const int s = row % seq; const int pos = axis ? (s & 63) : (s >> 6);
;                 const f32x4* rp = (const f32x4*)(rope + ((size_t)pos * 16 + i0) * 2);
; #pragma unroll
;                 for (int bj = 0; bj < 2; ++bj) { f32x4 v0 = acc[ai][bj][m][0], v1 = acc[ai][bj][m][1];
;                     const bool do_rope = (u.pn < 2) || (u.pn == 2 && bj == 0);
;                     if (do_rope) {
;                         const f32x4 cs0 = rp[0], cs1 = rp[1], cs2 = rp[2], cs3 = rp[3];
;                         f32x4 p0, p1;
; #pragma unroll
;                         for (int j = 0; j < 4; ++j) { p0[j] = __shfl_xor(v0[j], 32); p1[j] = __shfl_xor(v1[j], 32); }
;                         const float sc = (u.pn < 2) ? 0.125f * 1.4426950408889634f : 1.0f;
;                         v0[0] = (v0[0] * cs0[0] + sgn * p0[0] * cs0[1]) * sc; v0[1] = (v0[1] * cs0[2] + sgn * p0[1] * cs0[3]) * sc;
;                         v0[2] = (v0[2] * cs1[0] + sgn * p0[2] * cs1[1]) * sc; v0[3] = (v0[3] * cs1[2] + sgn * p0[3] * cs1[3]) * sc;
;                         v1[0] = (v1[0] * cs2[0] + sgn * p1[0] * cs2[1]) * sc; v1[1] = (v1[1] * cs2[2] + sgn * p1[1] * cs2[3]) * sc;
;                         v1[2] = (v1[2] * cs3[0] + sgn * p1[2] * cs3[1]) * sc; v1[3] = (v1[3] * cs3[2] + sgn * p1[3] * cs3[3]) * sc;
;                     }
;                     u32x4 w; w.x = cvt_pk_bf16(v0[0], v0[1]); w.y = cvt_pk_bf16(v0[2], v0[3]); w.z = cvt_pk_bf16(v1[0], v1[1]); w.w = cvt_pk_bf16(v1[2], v1[3]);
;                     *(u32x4*)(rowp + bj * HALF) = w; } }
	v_pk_mul_f32 v[110:111], v[110:111], s[24:25] op_sel_hi:[1,0]
	v_mov_b32_e32 v146, v104
	v_mov_b32_e32 v147, v105
	v_mov_b32_e32 v148, v106
	v_mov_b32_e32 v149, v107
	v_permlane32_swap_b32_e32 v104, v146
	v_permlane32_swap_b32_e32 v105, v147
	v_permlane32_swap_b32_e32 v106, v148
	v_permlane32_swap_b32_e32 v107, v149
	v_pk_mul_f32 v[146:147], v[146:147], v[232:233]
	v_pk_mul_f32 v[148:149], v[148:149], v[234:235]
	v_pk_fma_f32 v[104:105], v[104:105], v[228:229], v[146:147]
	v_pk_fma_f32 v[106:107], v[106:107], v[230:231], v[148:149]
	v_pk_mul_f32 v[104:105], v[104:105], s[24:25] op_sel_hi:[1,0]
	v_pk_mul_f32 v[106:107], v[106:107], s[24:25] op_sel_hi:[1,0]
	v_mov_b32_e32 v146, v100
	v_mov_b32_e32 v147, v101
	v_mov_b32_e32 v148, v102
	v_mov_b32_e32 v149, v103
	v_permlane32_swap_b32_e32 v100, v146
	v_permlane32_swap_b32_e32 v101, v147
	v_permlane32_swap_b32_e32 v102, v148
	v_permlane32_swap_b32_e32 v103, v149
	v_pk_mul_f32 v[146:147], v[146:147], v[200:201]
	v_pk_mul_f32 v[148:149], v[148:149], v[202:203]
	v_pk_fma_f32 v[100:101], v[100:101], v[224:225], v[146:147]
	v_pk_fma_f32 v[102:103], v[102:103], v[226:227], v[148:149]
	v_pk_mul_f32 v[100:101], v[100:101], s[24:25] op_sel_hi:[1,0]
	v_pk_mul_f32 v[102:103], v[102:103], s[24:25] op_sel_hi:[1,0]
	v_mov_b32_e32 v146, v96
	v_mov_b32_e32 v147, v97
	v_mov_b32_e32 v148, v98
	v_mov_b32_e32 v149, v99
	v_permlane32_swap_b32_e32 v96, v146
	v_permlane32_swap_b32_e32 v97, v147
	v_permlane32_swap_b32_e32 v98, v148
	v_permlane32_swap_b32_e32 v99, v149
	v_pk_mul_f32 v[146:147], v[146:147], v[232:233]
	v_pk_mul_f32 v[148:149], v[148:149], v[234:235]
	v_pk_fma_f32 v[96:97], v[96:97], v[228:229], v[146:147]
	v_pk_fma_f32 v[98:99], v[98:99], v[230:231], v[148:149]
	v_pk_mul_f32 v[96:97], v[96:97], s[24:25] op_sel_hi:[1,0]
	v_pk_mul_f32 v[98:99], v[98:99], s[24:25] op_sel_hi:[1,0]
	v_add_u32_e32 v151, 0xe000, v150
	v_cvt_pk_bf16_f32 v108, v108, v109
	v_cvt_pk_bf16_f32 v109, v110, v111
	v_cvt_pk_bf16_f32 v110, v104, v105
	v_cvt_pk_bf16_f32 v111, v106, v107
	global_store_dwordx4 v151, v[108:111], s[48:49]
	v_cvt_pk_bf16_f32 v100, v100, v101
	v_cvt_pk_bf16_f32 v101, v102, v103
	v_cvt_pk_bf16_f32 v102, v96, v97
	v_cvt_pk_bf16_f32 v103, v98, v99
	global_store_dwordx4 v151, v[100:103], s[48:49] offset:256
	s_waitcnt vmcnt(12)
	v_cndmask_b32_e64 v224, v209, v208, s[58:59]
	v_cndmask_b32_e64 v200, v208, -v209, s[58:59]
	v_cndmask_b32_e64 v225, v211, v210, s[58:59]
	v_cndmask_b32_e64 v201, v210, -v211, s[58:59]
	v_cndmask_b32_e64 v226, v213, v212, s[58:59]
	v_cndmask_b32_e64 v202, v212, -v213, s[58:59]
	v_cndmask_b32_e64 v227, v215, v214, s[58:59]
	v_cndmask_b32_e64 v203, v214, -v215, s[58:59]
	v_cndmask_b32_e64 v228, v217, v216, s[58:59]
	v_cndmask_b32_e64 v232, v216, -v217, s[58:59]
	v_cndmask_b32_e64 v229, v219, v218, s[58:59]
	v_cndmask_b32_e64 v233, v218, -v219, s[58:59]
	v_cndmask_b32_e64 v230, v221, v220, s[58:59]
	v_cndmask_b32_e64 v234, v220, -v221, s[58:59]
	v_cndmask_b32_e64 v231, v223, v222, s[58:59]
	v_cndmask_b32_e64 v235, v222, -v223, s[58:59]
	v_add_u32_e32 v237, 144, v167
	v_bfe_u32 v151, v237, 6, 8
	v_and_b32_e32 v237, 63, v237
	v_cndmask_b32_e64 v237, v237, v151, s[8:9]
	v_lshl_add_u32 v149, v237, 7, v236
	global_load_dwordx4 v[208:211], v149, s[60:61]
	global_load_dwordx4 v[212:215], v149, s[60:61] offset:16
	global_load_dwordx4 v[216:219], v149, s[60:61] offset:32
	global_load_dwordx4 v[220:223], v149, s[60:61] offset:48
	v_mov_b32_e32 v146, v92
	v_mov_b32_e32 v147, v93
	v_mov_b32_e32 v148, v94
	v_mov_b32_e32 v149, v95
	v_permlane32_swap_b32_e32 v92, v146
	v_permlane32_swap_b32_e32 v93, v147
	v_permlane32_swap_b32_e32 v94, v148
	v_permlane32_swap_b32_e32 v95, v149
	v_pk_mul_f32 v[146:147], v[146:147], v[200:201]
	v_pk_mul_f32 v[148:149], v[148:149], v[202:203]
	v_pk_fma_f32 v[92:93], v[92:93], v[224:225], v[146:147]
	v_pk_fma_f32 v[94:95], v[94:95], v[226:227], v[148:149]
	v_pk_mul_f32 v[92:93], v[92:93], s[24:25] op_sel_hi:[1,0]
	v_pk_mul_f32 v[94:95], v[94:95], s[24:25] op_sel_hi:[1,0]
	v_mov_b32_e32 v146, v88
	v_mov_b32_e32 v147, v89
	v_mov_b32_e32 v148, v90
	v_mov_b32_e32 v149, v91
	v_permlane32_swap_b32_e32 v88, v146
	v_permlane32_swap_b32_e32 v89, v147
	v_permlane32_swap_b32_e32 v90, v148
	v_permlane32_swap_b32_e32 v91, v149
	v_pk_mul_f32 v[146:147], v[146:147], v[232:233]
	v_pk_mul_f32 v[148:149], v[148:149], v[234:235]
	v_pk_fma_f32 v[88:89], v[88:89], v[228:229], v[146:147]
	v_pk_fma_f32 v[90:91], v[90:91], v[230:231], v[148:149]
	v_pk_mul_f32 v[88:89], v[88:89], s[24:25] op_sel_hi:[1,0]
	v_pk_mul_f32 v[90:91], v[90:91], s[24:25] op_sel_hi:[1,0]
	v_mov_b32_e32 v146, v84
	v_mov_b32_e32 v147, v85
	v_mov_b32_e32 v148, v86
	v_mov_b32_e32 v149, v87
	v_permlane32_swap_b32_e32 v84, v146
	v_permlane32_swap_b32_e32 v85, v147
	v_permlane32_swap_b32_e32 v86, v148
	v_permlane32_swap_b32_e32 v87, v149
	v_pk_mul_f32 v[146:147], v[146:147], v[200:201]
	v_pk_mul_f32 v[148:149], v[148:149], v[202:203]
	v_pk_fma_f32 v[84:85], v[84:85], v[224:225], v[146:147]
	v_pk_fma_f32 v[86:87], v[86:87], v[226:227], v[148:149]
	v_pk_mul_f32 v[84:85], v[84:85], s[24:25] op_sel_hi:[1,0]
	v_pk_mul_f32 v[86:87], v[86:87], s[24:25] op_sel_hi:[1,0]
	v_mov_b32_e32 v146, v80
	v_mov_b32_e32 v147, v81
	v_mov_b32_e32 v148, v82
	v_mov_b32_e32 v149, v83
	v_permlane32_swap_b32_e32 v80, v146
	v_permlane32_swap_b32_e32 v81, v147
	v_permlane32_swap_b32_e32 v82, v148
	v_permlane32_swap_b32_e32 v83, v149
	v_pk_mul_f32 v[146:147], v[146:147], v[232:233]
	v_pk_mul_f32 v[148:149], v[148:149], v[234:235]
	v_pk_fma_f32 v[80:81], v[80:81], v[228:229], v[146:147]
	v_pk_fma_f32 v[82:83], v[82:83], v[230:231], v[148:149]
	v_pk_mul_f32 v[80:81], v[80:81], s[24:25] op_sel_hi:[1,0]
	v_pk_mul_f32 v[82:83], v[82:83], s[24:25] op_sel_hi:[1,0]
	v_add_u32_e32 v151, 0x1c000, v150
	v_cvt_pk_bf16_f32 v92, v92, v93
	v_cvt_pk_bf16_f32 v93, v94, v95
	v_cvt_pk_bf16_f32 v94, v88, v89
	v_cvt_pk_bf16_f32 v95, v90, v91
	global_store_dwordx4 v151, v[92:95], s[48:49]
	v_cvt_pk_bf16_f32 v84, v84, v85
	v_cvt_pk_bf16_f32 v85, v86, v87
	v_cvt_pk_bf16_f32 v86, v80, v81
	v_cvt_pk_bf16_f32 v87, v82, v83
	global_store_dwordx4 v151, v[84:87], s[48:49] offset:256
	s_waitcnt vmcnt(14)
; __device__ __forceinline__ unsigned cvt_pk_bf16(float lo, float hi) { f32x2_t v = {lo, hi}; bf16x2_t b = __builtin_convertvector(v, bf16x2_t); return __builtin_bit_cast(unsigned, b); }
;     __device__ __forceinline__ void operator()(const f32x4 (&acc)[2][2][4][2], const Unit& u, int wr, int wc, int fr, int fq) const {
;     ...
;             for (int m = 0; m < 4; ++m) { const int row = row0 + ai * HALF + m * 16; bf16_t* rowp = O + (size_t)row * ldc + col0;
;                 const int s = row % seq; const int pos = axis ? (s & 63) : (s >> 6);
;                 const f32x4* rp = (const f32x4*)(rope + ((size_t)pos * 16 + i0) * 2);
; #pragma unroll
;                 for (int bj = 0; bj < 2; ++bj) { f32x4 v0 = acc[ai][bj][m][0], v1 = acc[ai][bj][m][1];
;                     const bool do_rope = (u.pn < 2) || (u.pn == 2 && bj == 0);
;                     if (do_rope) {
;                         const f32x4 cs0 = rp[0], cs1 = rp[1], cs2 = rp[2], cs3 = rp[3];
;                         f32x4 p0, p1;
; #pragma unroll
;                         for (int j = 0; j < 4; ++j) { p0[j] = __shfl_xor(v0[j], 32); p1[j] = __shfl_xor(v1[j], 32); }
;                         const float sc = (u.pn < 2) ? 0.125f * 1.4426950408889634f : 1.0f;
;                         v0[0] = (v0[0] * cs0[0] + sgn * p0[0] * cs0[1]) * sc; v0[1] = (v0[1] * cs0[2] + sgn * p0[1] * cs0[3]) * sc;
;                         v0[2] = (v0[2] * cs1[0] + sgn * p0[2] * cs1[1]) * sc; v0[3] = (v0[3] * cs1[2] + sgn * p0[3] * cs1[3]) * sc;
;                         v1[0] = (v1[0] * cs2[0] + sgn * p1[0] * cs2[1]) * sc; v1[1] = (v1[1] * cs2[2] + sgn * p1[1] * cs2[3]) * sc;
;                         v1[2] = (v1[2] * cs3[0] + sgn * p1[2] * cs3[1]) * sc; v1[3] = (v1[3] * cs3[2] + sgn * p1[3] * cs3[3]) * sc;
;                     }
;                     u32x4 w; w.x = cvt_pk_bf16(v0[0], v0[1]); w.y = cvt_pk_bf16(v0[2], v0[3]); w.z = cvt_pk_bf16(v1[0], v1[1]); w.w = cvt_pk_bf16(v1[2], v1[3]);
;                     *(u32x4*)(rowp + bj * HALF) = w; } }
	v_cndmask_b32_e64 v224, v169, v168, s[58:59]
	v_cndmask_b32_e64 v200, v168, -v169, s[58:59]
	v_cndmask_b32_e64 v225, v171, v170, s[58:59]
	v_cndmask_b32_e64 v201, v170, -v171, s[58:59]
	v_cndmask_b32_e64 v226, v173, v172, s[58:59]
	v_cndmask_b32_e64 v202, v172, -v173, s[58:59]
	v_cndmask_b32_e64 v227, v175, v174, s[58:59]
	v_cndmask_b32_e64 v203, v174, -v175, s[58:59]
	v_cndmask_b32_e64 v228, v177, v176, s[58:59]
	v_cndmask_b32_e64 v232, v176, -v177, s[58:59]
	v_cndmask_b32_e64 v229, v179, v178, s[58:59]
	v_cndmask_b32_e64 v233, v178, -v179, s[58:59]
	v_cndmask_b32_e64 v230, v181, v180, s[58:59]
	v_cndmask_b32_e64 v234, v180, -v181, s[58:59]
	v_cndmask_b32_e64 v231, v183, v182, s[58:59]
	v_cndmask_b32_e64 v235, v182, -v183, s[58:59]
	v_add_u32_e32 v237, 160, v167
	v_bfe_u32 v151, v237, 6, 8
	v_and_b32_e32 v237, 63, v237
	v_cndmask_b32_e64 v237, v237, v151, s[8:9]
	v_lshl_add_u32 v149, v237, 7, v236
	global_load_dwordx4 v[168:171], v149, s[60:61]
	global_load_dwordx4 v[172:175], v149, s[60:61] offset:16
	global_load_dwordx4 v[176:179], v149, s[60:61] offset:32
	global_load_dwordx4 v[180:183], v149, s[60:61] offset:48
	v_mov_b32_e32 v146, v76
	v_mov_b32_e32 v147, v77
	v_mov_b32_e32 v148, v78
	v_mov_b32_e32 v149, v79
	v_permlane32_swap_b32_e32 v76, v146
	v_permlane32_swap_b32_e32 v77, v147
	v_permlane32_swap_b32_e32 v78, v148
	v_permlane32_swap_b32_e32 v79, v149
	v_pk_mul_f32 v[146:147], v[146:147], v[200:201]
	v_pk_mul_f32 v[148:149], v[148:149], v[202:203]
	v_pk_fma_f32 v[76:77], v[76:77], v[224:225], v[146:147]
	v_pk_fma_f32 v[78:79], v[78:79], v[226:227], v[148:149]
	v_pk_mul_f32 v[76:77], v[76:77], s[24:25] op_sel_hi:[1,0]
	v_pk_mul_f32 v[78:79], v[78:79], s[24:25] op_sel_hi:[1,0]
	v_mov_b32_e32 v146, v72
	v_mov_b32_e32 v147, v73
	v_mov_b32_e32 v148, v74
	v_mov_b32_e32 v149, v75
	v_permlane32_swap_b32_e32 v72, v146
	v_permlane32_swap_b32_e32 v73, v147
	v_permlane32_swap_b32_e32 v74, v148
	v_permlane32_swap_b32_e32 v75, v149
	v_pk_mul_f32 v[146:147], v[146:147], v[232:233]
	v_pk_mul_f32 v[148:149], v[148:149], v[234:235]
	v_pk_fma_f32 v[72:73], v[72:73], v[228:229], v[146:147]
	v_pk_fma_f32 v[74:75], v[74:75], v[230:231], v[148:149]
	v_pk_mul_f32 v[72:73], v[72:73], s[24:25] op_sel_hi:[1,0]
	v_pk_mul_f32 v[74:75], v[74:75], s[24:25] op_sel_hi:[1,0]
	v_mov_b32_e32 v146, v68
	v_mov_b32_e32 v147, v69
	v_mov_b32_e32 v148, v70
	v_mov_b32_e32 v149, v71
	v_permlane32_swap_b32_e32 v68, v146
	v_permlane32_swap_b32_e32 v69, v147
	v_permlane32_swap_b32_e32 v70, v148
	v_permlane32_swap_b32_e32 v71, v149
	v_pk_mul_f32 v[146:147], v[146:147], v[200:201]
	v_pk_mul_f32 v[148:149], v[148:149], v[202:203]
	v_pk_fma_f32 v[68:69], v[68:69], v[224:225], v[146:147]
	v_pk_fma_f32 v[70:71], v[70:71], v[226:227], v[148:149]
	v_pk_mul_f32 v[68:69], v[68:69], s[24:25] op_sel_hi:[1,0]
	v_pk_mul_f32 v[70:71], v[70:71], s[24:25] op_sel_hi:[1,0]
	v_mov_b32_e32 v146, v64
	v_mov_b32_e32 v147, v65
	v_mov_b32_e32 v148, v66
	v_mov_b32_e32 v149, v67
	v_permlane32_swap_b32_e32 v64, v146
	v_permlane32_swap_b32_e32 v65, v147
	v_permlane32_swap_b32_e32 v66, v148
	v_permlane32_swap_b32_e32 v67, v149
	v_pk_mul_f32 v[146:147], v[146:147], v[232:233]
	v_pk_mul_f32 v[148:149], v[148:149], v[234:235]
	v_pk_fma_f32 v[64:65], v[64:65], v[228:229], v[146:147]
	v_pk_fma_f32 v[66:67], v[66:67], v[230:231], v[148:149]
	v_pk_mul_f32 v[64:65], v[64:65], s[24:25] op_sel_hi:[1,0]
	v_pk_mul_f32 v[66:67], v[66:67], s[24:25] op_sel_hi:[1,0]
	v_add_u32_e32 v151, 0x2a000, v150
	v_cvt_pk_bf16_f32 v76, v76, v77
	v_cvt_pk_bf16_f32 v77, v78, v79
	v_cvt_pk_bf16_f32 v78, v72, v73
	v_cvt_pk_bf16_f32 v79, v74, v75
	global_store_dwordx4 v151, v[76:79], s[48:49]
	v_cvt_pk_bf16_f32 v68, v68, v69
	v_cvt_pk_bf16_f32 v69, v70, v71
	v_cvt_pk_bf16_f32 v70, v64, v65
	v_cvt_pk_bf16_f32 v71, v66, v67
	global_store_dwordx4 v151, v[68:71], s[48:49] offset:256
	s_waitcnt vmcnt(14)
	v_cndmask_b32_e64 v224, v185, v184, s[58:59]
	v_cndmask_b32_e64 v200, v184, -v185, s[58:59]
	v_cndmask_b32_e64 v225, v187, v186, s[58:59]
	v_cndmask_b32_e64 v201, v186, -v187, s[58:59]
	v_cndmask_b32_e64 v226, v189, v188, s[58:59]
	v_cndmask_b32_e64 v202, v188, -v189, s[58:59]
	v_cndmask_b32_e64 v227, v191, v190, s[58:59]
	v_cndmask_b32_e64 v203, v190, -v191, s[58:59]
	v_cndmask_b32_e64 v228, v193, v192, s[58:59]
	v_cndmask_b32_e64 v232, v192, -v193, s[58:59]
	v_cndmask_b32_e64 v229, v195, v194, s[58:59]
	v_cndmask_b32_e64 v233, v194, -v195, s[58:59]
	v_cndmask_b32_e64 v230, v197, v196, s[58:59]
	v_cndmask_b32_e64 v234, v196, -v197, s[58:59]
	v_cndmask_b32_e64 v231, v199, v198, s[58:59]
	v_cndmask_b32_e64 v235, v198, -v199, s[58:59]
	v_add_u32_e32 v237, 176, v167
	v_bfe_u32 v151, v237, 6, 8
	v_and_b32_e32 v237, 63, v237
	v_cndmask_b32_e64 v237, v237, v151, s[8:9]
	v_lshl_add_u32 v149, v237, 7, v236
	global_load_dwordx4 v[184:187], v149, s[60:61]
	global_load_dwordx4 v[188:191], v149, s[60:61] offset:16
	global_load_dwordx4 v[192:195], v149, s[60:61] offset:32
	global_load_dwordx4 v[196:199], v149, s[60:61] offset:48
	v_mov_b32_e32 v146, v60
	v_mov_b32_e32 v147, v61
	v_mov_b32_e32 v148, v62
	v_mov_b32_e32 v149, v63
	v_permlane32_swap_b32_e32 v60, v146
	v_permlane32_swap_b32_e32 v61, v147
	v_permlane32_swap_b32_e32 v62, v148
	v_permlane32_swap_b32_e32 v63, v149
	v_pk_mul_f32 v[146:147], v[146:147], v[200:201]
	v_pk_mul_f32 v[148:149], v[148:149], v[202:203]
	v_pk_fma_f32 v[60:61], v[60:61], v[224:225], v[146:147]
	v_pk_fma_f32 v[62:63], v[62:63], v[226:227], v[148:149]
	v_pk_mul_f32 v[60:61], v[60:61], s[24:25] op_sel_hi:[1,0]
	v_pk_mul_f32 v[62:63], v[62:63], s[24:25] op_sel_hi:[1,0]
	v_mov_b32_e32 v146, v56
	v_mov_b32_e32 v147, v57
; __device__ __forceinline__ unsigned cvt_pk_bf16(float lo, float hi) { f32x2_t v = {lo, hi}; bf16x2_t b = __builtin_convertvector(v, bf16x2_t); return __builtin_bit_cast(unsigned, b); }
;     __device__ __forceinline__ void operator()(const f32x4 (&acc)[2][2][4][2], const Unit& u, int wr, int wc, int fr, int fq) const {
;     ...
;             for (int m = 0; m < 4; ++m) { const int row = row0 + ai * HALF + m * 16; bf16_t* rowp = O + (size_t)row * ldc + col0;
;                 const int s = row % seq; const int pos = axis ? (s & 63) : (s >> 6);
;                 const f32x4* rp = (const f32x4*)(rope + ((size_t)pos * 16 + i0) * 2);
; #pragma unroll
;                 for (int bj = 0; bj < 2; ++bj) { f32x4 v0 = acc[ai][bj][m][0], v1 = acc[ai][bj][m][1];
;                     const bool do_rope = (u.pn < 2) || (u.pn == 2 && bj == 0);
;                     if (do_rope) {
;                         const f32x4 cs0 = rp[0], cs1 = rp[1], cs2 = rp[2], cs3 = rp[3];
;                         f32x4 p0, p1;
; #pragma unroll
;                         for (int j = 0; j < 4; ++j) { p0[j] = __shfl_xor(v0[j], 32); p1[j] = __shfl_xor(v1[j], 32); }
;                         const float sc = (u.pn < 2) ? 0.125f * 1.4426950408889634f : 1.0f;
;                         v0[0] = (v0[0] * cs0[0] + sgn * p0[0] * cs0[1]) * sc; v0[1] = (v0[1] * cs0[2] + sgn * p0[1] * cs0[3]) * sc;
;                         v0[2] = (v0[2] * cs1[0] + sgn * p0[2] * cs1[1]) * sc; v0[3] = (v0[3] * cs1[2] + sgn * p0[3] * cs1[3]) * sc;
;                         v1[0] = (v1[0] * cs2[0] + sgn * p1[0] * cs2[1]) * sc; v1[1] = (v1[1] * cs2[2] + sgn * p1[1] * cs2[3]) * sc;
;                         v1[2] = (v1[2] * cs3[0] + sgn * p1[2] * cs3[1]) * sc; v1[3] = (v1[3] * cs3[2] + sgn * p1[3] * cs3[3]) * sc;
;                     }
;                     u32x4 w; w.x = cvt_pk_bf16(v0[0], v0[1]); w.y = cvt_pk_bf16(v0[2], v0[3]); w.z = cvt_pk_bf16(v1[0], v1[1]); w.w = cvt_pk_bf16(v1[2], v1[3]);
;                     *(u32x4*)(rowp + bj * HALF) = w; } }
	v_mov_b32_e32 v148, v58
	v_mov_b32_e32 v149, v59
	v_permlane32_swap_b32_e32 v56, v146
	v_permlane32_swap_b32_e32 v57, v147
	v_permlane32_swap_b32_e32 v58, v148
	v_permlane32_swap_b32_e32 v59, v149
	v_pk_mul_f32 v[146:147], v[146:147], v[232:233]
	v_pk_mul_f32 v[148:149], v[148:149], v[234:235]
	v_pk_fma_f32 v[56:57], v[56:57], v[228:229], v[146:147]
	v_pk_fma_f32 v[58:59], v[58:59], v[230:231], v[148:149]
	v_pk_mul_f32 v[56:57], v[56:57], s[24:25] op_sel_hi:[1,0]
	v_pk_mul_f32 v[58:59], v[58:59], s[24:25] op_sel_hi:[1,0]
	v_mov_b32_e32 v146, v52
	v_mov_b32_e32 v147, v53
	v_mov_b32_e32 v148, v54
	v_mov_b32_e32 v149, v55
	v_permlane32_swap_b32_e32 v52, v146
	v_permlane32_swap_b32_e32 v53, v147
	v_permlane32_swap_b32_e32 v54, v148
	v_permlane32_swap_b32_e32 v55, v149
	v_pk_mul_f32 v[146:147], v[146:147], v[200:201]
	v_pk_mul_f32 v[148:149], v[148:149], v[202:203]
	v_pk_fma_f32 v[52:53], v[52:53], v[224:225], v[146:147]
	v_pk_fma_f32 v[54:55], v[54:55], v[226:227], v[148:149]
	v_pk_mul_f32 v[52:53], v[52:53], s[24:25] op_sel_hi:[1,0]
	v_pk_mul_f32 v[54:55], v[54:55], s[24:25] op_sel_hi:[1,0]
	v_mov_b32_e32 v146, v48
	v_mov_b32_e32 v147, v49
	v_mov_b32_e32 v148, v50
	v_mov_b32_e32 v149, v51
	v_permlane32_swap_b32_e32 v48, v146
	v_permlane32_swap_b32_e32 v49, v147
	v_permlane32_swap_b32_e32 v50, v148
	v_permlane32_swap_b32_e32 v51, v149
	v_pk_mul_f32 v[146:147], v[146:147], v[232:233]
	v_pk_mul_f32 v[148:149], v[148:149], v[234:235]
	v_pk_fma_f32 v[48:49], v[48:49], v[228:229], v[146:147]
	v_pk_fma_f32 v[50:51], v[50:51], v[230:231], v[148:149]
	v_pk_mul_f32 v[48:49], v[48:49], s[24:25] op_sel_hi:[1,0]
	v_pk_mul_f32 v[50:51], v[50:51], s[24:25] op_sel_hi:[1,0]
	v_add_u32_e32 v151, 0x70000, v150
	v_cvt_pk_bf16_f32 v60, v60, v61
	v_cvt_pk_bf16_f32 v61, v62, v63
	v_cvt_pk_bf16_f32 v62, v56, v57
	v_cvt_pk_bf16_f32 v63, v58, v59
	global_store_dwordx4 v151, v[60:63], s[48:49]
	v_cvt_pk_bf16_f32 v52, v52, v53
	v_cvt_pk_bf16_f32 v53, v54, v55
	v_cvt_pk_bf16_f32 v54, v48, v49
	v_cvt_pk_bf16_f32 v55, v50, v51
	global_store_dwordx4 v151, v[52:55], s[48:49] offset:256
	s_waitcnt vmcnt(14)
	v_cndmask_b32_e64 v224, v209, v208, s[58:59]
	v_cndmask_b32_e64 v200, v208, -v209, s[58:59]
	v_cndmask_b32_e64 v225, v211, v210, s[58:59]
	v_cndmask_b32_e64 v201, v210, -v211, s[58:59]
	v_cndmask_b32_e64 v226, v213, v212, s[58:59]
	v_cndmask_b32_e64 v202, v212, -v213, s[58:59]
	v_cndmask_b32_e64 v227, v215, v214, s[58:59]
	v_cndmask_b32_e64 v203, v214, -v215, s[58:59]
	v_cndmask_b32_e64 v228, v217, v216, s[58:59]
	v_cndmask_b32_e64 v232, v216, -v217, s[58:59]
	v_cndmask_b32_e64 v229, v219, v218, s[58:59]
	v_cndmask_b32_e64 v233, v218, -v219, s[58:59]
	v_cndmask_b32_e64 v230, v221, v220, s[58:59]
	v_cndmask_b32_e64 v234, v220, -v221, s[58:59]
	v_cndmask_b32_e64 v231, v223, v222, s[58:59]
	v_cndmask_b32_e64 v235, v222, -v223, s[58:59]
	v_mov_b32_e32 v146, v44
	v_mov_b32_e32 v147, v45
	v_mov_b32_e32 v148, v46
	v_mov_b32_e32 v149, v47
	v_permlane32_swap_b32_e32 v44, v146
	v_permlane32_swap_b32_e32 v45, v147
	v_permlane32_swap_b32_e32 v46, v148
	v_permlane32_swap_b32_e32 v47, v149
	v_pk_mul_f32 v[146:147], v[146:147], v[200:201]
	v_pk_mul_f32 v[148:149], v[148:149], v[202:203]
	v_pk_fma_f32 v[44:45], v[44:45], v[224:225], v[146:147]
	v_pk_fma_f32 v[46:47], v[46:47], v[226:227], v[148:149]
	v_pk_mul_f32 v[44:45], v[44:45], s[24:25] op_sel_hi:[1,0]
	v_pk_mul_f32 v[46:47], v[46:47], s[24:25] op_sel_hi:[1,0]
	v_mov_b32_e32 v146, v40
	v_mov_b32_e32 v147, v41
	v_mov_b32_e32 v148, v42
	v_mov_b32_e32 v149, v43
	v_permlane32_swap_b32_e32 v40, v146
	v_permlane32_swap_b32_e32 v41, v147
	v_permlane32_swap_b32_e32 v42, v148
	v_permlane32_swap_b32_e32 v43, v149
	v_pk_mul_f32 v[146:147], v[146:147], v[232:233]
	v_pk_mul_f32 v[148:149], v[148:149], v[234:235]
	v_pk_fma_f32 v[40:41], v[40:41], v[228:229], v[146:147]
	v_pk_fma_f32 v[42:43], v[42:43], v[230:231], v[148:149]
	v_pk_mul_f32 v[40:41], v[40:41], s[24:25] op_sel_hi:[1,0]
	v_pk_mul_f32 v[42:43], v[42:43], s[24:25] op_sel_hi:[1,0]
	v_mov_b32_e32 v146, v36
	v_mov_b32_e32 v147, v37
	v_mov_b32_e32 v148, v38
	v_mov_b32_e32 v149, v39
	v_permlane32_swap_b32_e32 v36, v146
	v_permlane32_swap_b32_e32 v37, v147
	v_permlane32_swap_b32_e32 v38, v148
	v_permlane32_swap_b32_e32 v39, v149
	v_pk_mul_f32 v[146:147], v[146:147], v[200:201]
	v_pk_mul_f32 v[148:149], v[148:149], v[202:203]
	v_pk_fma_f32 v[36:37], v[36:37], v[224:225], v[146:147]
	v_pk_fma_f32 v[38:39], v[38:39], v[226:227], v[148:149]
	v_pk_mul_f32 v[36:37], v[36:37], s[24:25] op_sel_hi:[1,0]
	v_pk_mul_f32 v[38:39], v[38:39], s[24:25] op_sel_hi:[1,0]
	v_mov_b32_e32 v146, v32
	v_mov_b32_e32 v147, v33
	v_mov_b32_e32 v148, v34
	v_mov_b32_e32 v149, v35
	v_permlane32_swap_b32_e32 v32, v146
	v_permlane32_swap_b32_e32 v33, v147
	v_permlane32_swap_b32_e32 v34, v148
	v_permlane32_swap_b32_e32 v35, v149
	v_pk_mul_f32 v[146:147], v[146:147], v[232:233]
	v_pk_mul_f32 v[148:149], v[148:149], v[234:235]
	v_pk_fma_f32 v[32:33], v[32:33], v[228:229], v[146:147]
	v_pk_fma_f32 v[34:35], v[34:35], v[230:231], v[148:149]
	v_pk_mul_f32 v[32:33], v[32:33], s[24:25] op_sel_hi:[1,0]
	v_pk_mul_f32 v[34:35], v[34:35], s[24:25] op_sel_hi:[1,0]
	v_add_u32_e32 v151, 0x7e000, v150
	v_cvt_pk_bf16_f32 v44, v44, v45
	v_cvt_pk_bf16_f32 v45, v46, v47
	v_cvt_pk_bf16_f32 v46, v40, v41
	v_cvt_pk_bf16_f32 v47, v42, v43
	global_store_dwordx4 v151, v[44:47], s[48:49]
	v_cvt_pk_bf16_f32 v36, v36, v37
	v_cvt_pk_bf16_f32 v37, v38, v39
	v_cvt_pk_bf16_f32 v38, v32, v33
	v_cvt_pk_bf16_f32 v39, v34, v35
	global_store_dwordx4 v151, v[36:39], s[48:49] offset:256
	s_waitcnt vmcnt(10)
; __device__ __forceinline__ unsigned cvt_pk_bf16(float lo, float hi) { f32x2_t v = {lo, hi}; bf16x2_t b = __builtin_convertvector(v, bf16x2_t); return __builtin_bit_cast(unsigned, b); }
;     __device__ __forceinline__ void operator()(const f32x4 (&acc)[2][2][4][2], const Unit& u, int wr, int wc, int fr, int fq) const {
;     ...
;             for (int m = 0; m < 4; ++m) { const int row = row0 + ai * HALF + m * 16; bf16_t* rowp = O + (size_t)row * ldc + col0;
;                 const int s = row % seq; const int pos = axis ? (s & 63) : (s >> 6);
;                 const f32x4* rp = (const f32x4*)(rope + ((size_t)pos * 16 + i0) * 2);
; #pragma unroll
;                 for (int bj = 0; bj < 2; ++bj) { f32x4 v0 = acc[ai][bj][m][0], v1 = acc[ai][bj][m][1];
;                     const bool do_rope = (u.pn < 2) || (u.pn == 2 && bj == 0);
;                     if (do_rope) {
;                         const f32x4 cs0 = rp[0], cs1 = rp[1], cs2 = rp[2], cs3 = rp[3];
;                         f32x4 p0, p1;
; #pragma unroll
;                         for (int j = 0; j < 4; ++j) { p0[j] = __shfl_xor(v0[j], 32); p1[j] = __shfl_xor(v1[j], 32); }
;                         const float sc = (u.pn < 2) ? 0.125f * 1.4426950408889634f : 1.0f;
;                         v0[0] = (v0[0] * cs0[0] + sgn * p0[0] * cs0[1]) * sc; v0[1] = (v0[1] * cs0[2] + sgn * p0[1] * cs0[3]) * sc;
;                         v0[2] = (v0[2] * cs1[0] + sgn * p0[2] * cs1[1]) * sc; v0[3] = (v0[3] * cs1[2] + sgn * p0[3] * cs1[3]) * sc;
;                         v1[0] = (v1[0] * cs2[0] + sgn * p1[0] * cs2[1]) * sc; v1[1] = (v1[1] * cs2[2] + sgn * p1[1] * cs2[3]) * sc;
;                         v1[2] = (v1[2] * cs3[0] + sgn * p1[2] * cs3[1]) * sc; v1[3] = (v1[3] * cs3[2] + sgn * p1[3] * cs3[3]) * sc;
;                     }
;                     u32x4 w; w.x = cvt_pk_bf16(v0[0], v0[1]); w.y = cvt_pk_bf16(v0[2], v0[3]); w.z = cvt_pk_bf16(v1[0], v1[1]); w.w = cvt_pk_bf16(v1[2], v1[3]);
;                     *(u32x4*)(rowp + bj * HALF) = w; } }
	v_cndmask_b32_e64 v224, v169, v168, s[58:59]
	v_cndmask_b32_e64 v200, v168, -v169, s[58:59]
	v_cndmask_b32_e64 v225, v171, v170, s[58:59]
	v_cndmask_b32_e64 v201, v170, -v171, s[58:59]
	v_cndmask_b32_e64 v226, v173, v172, s[58:59]
	v_cndmask_b32_e64 v202, v172, -v173, s[58:59]
	v_cndmask_b32_e64 v227, v175, v174, s[58:59]
	v_cndmask_b32_e64 v203, v174, -v175, s[58:59]
	v_cndmask_b32_e64 v228, v177, v176, s[58:59]
	v_cndmask_b32_e64 v232, v176, -v177, s[58:59]
	v_cndmask_b32_e64 v229, v179, v178, s[58:59]
	v_cndmask_b32_e64 v233, v178, -v179, s[58:59]
	v_cndmask_b32_e64 v230, v181, v180, s[58:59]
	v_cndmask_b32_e64 v234, v180, -v181, s[58:59]
	v_cndmask_b32_e64 v231, v183, v182, s[58:59]
	v_cndmask_b32_e64 v235, v182, -v183, s[58:59]
	v_mov_b32_e32 v146, v28
	v_mov_b32_e32 v147, v29
	v_mov_b32_e32 v148, v30
	v_mov_b32_e32 v149, v31
	v_permlane32_swap_b32_e32 v28, v146
	v_permlane32_swap_b32_e32 v29, v147
	v_permlane32_swap_b32_e32 v30, v148
	v_permlane32_swap_b32_e32 v31, v149
	v_pk_mul_f32 v[146:147], v[146:147], v[200:201]
	v_pk_mul_f32 v[148:149], v[148:149], v[202:203]
	v_pk_fma_f32 v[28:29], v[28:29], v[224:225], v[146:147]
	v_pk_fma_f32 v[30:31], v[30:31], v[226:227], v[148:149]
	v_pk_mul_f32 v[28:29], v[28:29], s[24:25] op_sel_hi:[1,0]
	v_pk_mul_f32 v[30:31], v[30:31], s[24:25] op_sel_hi:[1,0]
	v_mov_b32_e32 v146, v24
	v_mov_b32_e32 v147, v25
	v_mov_b32_e32 v148, v26
	v_mov_b32_e32 v149, v27
	v_permlane32_swap_b32_e32 v24, v146
	v_permlane32_swap_b32_e32 v25, v147
	v_permlane32_swap_b32_e32 v26, v148
	v_permlane32_swap_b32_e32 v27, v149
	v_pk_mul_f32 v[146:147], v[146:147], v[232:233]
	v_pk_mul_f32 v[148:149], v[148:149], v[234:235]
	v_pk_fma_f32 v[24:25], v[24:25], v[228:229], v[146:147]
	v_pk_fma_f32 v[26:27], v[26:27], v[230:231], v[148:149]
	v_pk_mul_f32 v[24:25], v[24:25], s[24:25] op_sel_hi:[1,0]
	v_pk_mul_f32 v[26:27], v[26:27], s[24:25] op_sel_hi:[1,0]
	v_mov_b32_e32 v146, v20
	v_mov_b32_e32 v147, v21
	v_mov_b32_e32 v148, v22
	v_mov_b32_e32 v149, v23
	v_permlane32_swap_b32_e32 v20, v146
	v_permlane32_swap_b32_e32 v21, v147
	v_permlane32_swap_b32_e32 v22, v148
	v_permlane32_swap_b32_e32 v23, v149
	v_pk_mul_f32 v[146:147], v[146:147], v[200:201]
	v_pk_mul_f32 v[148:149], v[148:149], v[202:203]
	v_pk_fma_f32 v[20:21], v[20:21], v[224:225], v[146:147]
	v_pk_fma_f32 v[22:23], v[22:23], v[226:227], v[148:149]
	v_pk_mul_f32 v[20:21], v[20:21], s[24:25] op_sel_hi:[1,0]
	v_pk_mul_f32 v[22:23], v[22:23], s[24:25] op_sel_hi:[1,0]
	v_mov_b32_e32 v146, v16
	v_mov_b32_e32 v147, v17
	v_mov_b32_e32 v148, v18
	v_mov_b32_e32 v149, v19
	v_permlane32_swap_b32_e32 v16, v146
	v_permlane32_swap_b32_e32 v17, v147
	v_permlane32_swap_b32_e32 v18, v148
	v_permlane32_swap_b32_e32 v19, v149
	v_pk_mul_f32 v[146:147], v[146:147], v[232:233]
	v_pk_mul_f32 v[148:149], v[148:149], v[234:235]
	v_pk_fma_f32 v[16:17], v[16:17], v[228:229], v[146:147]
	v_pk_fma_f32 v[18:19], v[18:19], v[230:231], v[148:149]
	v_pk_mul_f32 v[16:17], v[16:17], s[24:25] op_sel_hi:[1,0]
	v_pk_mul_f32 v[18:19], v[18:19], s[24:25] op_sel_hi:[1,0]
	v_add_u32_e32 v151, 0x8c000, v150
	v_cvt_pk_bf16_f32 v28, v28, v29
	v_cvt_pk_bf16_f32 v29, v30, v31
	v_cvt_pk_bf16_f32 v30, v24, v25
	v_cvt_pk_bf16_f32 v31, v26, v27
	global_store_dwordx4 v151, v[28:31], s[48:49]
	v_cvt_pk_bf16_f32 v20, v20, v21
	v_cvt_pk_bf16_f32 v21, v22, v23
	v_cvt_pk_bf16_f32 v22, v16, v17
	v_cvt_pk_bf16_f32 v23, v18, v19
	global_store_dwordx4 v151, v[20:23], s[48:49] offset:256
	s_waitcnt vmcnt(6)
	v_cndmask_b32_e64 v224, v185, v184, s[58:59]
	v_cndmask_b32_e64 v200, v184, -v185, s[58:59]
	v_cndmask_b32_e64 v225, v187, v186, s[58:59]
	v_cndmask_b32_e64 v201, v186, -v187, s[58:59]
	v_cndmask_b32_e64 v226, v189, v188, s[58:59]
	v_cndmask_b32_e64 v202, v188, -v189, s[58:59]
	v_cndmask_b32_e64 v227, v191, v190, s[58:59]
	v_cndmask_b32_e64 v203, v190, -v191, s[58:59]
	v_cndmask_b32_e64 v228, v193, v192, s[58:59]
	v_cndmask_b32_e64 v232, v192, -v193, s[58:59]
	v_cndmask_b32_e64 v229, v195, v194, s[58:59]
	v_cndmask_b32_e64 v233, v194, -v195, s[58:59]
	v_cndmask_b32_e64 v230, v197, v196, s[58:59]
	v_cndmask_b32_e64 v234, v196, -v197, s[58:59]
	v_cndmask_b32_e64 v231, v199, v198, s[58:59]
	v_cndmask_b32_e64 v235, v198, -v199, s[58:59]
	v_mov_b32_e32 v146, v12
	v_mov_b32_e32 v147, v13
	v_mov_b32_e32 v148, v14
	v_mov_b32_e32 v149, v15
	v_permlane32_swap_b32_e32 v12, v146
	v_permlane32_swap_b32_e32 v13, v147
	v_permlane32_swap_b32_e32 v14, v148
	v_permlane32_swap_b32_e32 v15, v149
	v_pk_mul_f32 v[146:147], v[146:147], v[200:201]
	v_pk_mul_f32 v[148:149], v[148:149], v[202:203]
	v_pk_fma_f32 v[12:13], v[12:13], v[224:225], v[146:147]
	v_pk_fma_f32 v[14:15], v[14:15], v[226:227], v[148:149]
	v_pk_mul_f32 v[12:13], v[12:13], s[24:25] op_sel_hi:[1,0]
	v_pk_mul_f32 v[14:15], v[14:15], s[24:25] op_sel_hi:[1,0]
	v_mov_b32_e32 v146, v8
	v_mov_b32_e32 v147, v9
	v_mov_b32_e32 v148, v10
	v_mov_b32_e32 v149, v11
	v_permlane32_swap_b32_e32 v8, v146
	v_permlane32_swap_b32_e32 v9, v147
	v_permlane32_swap_b32_e32 v10, v148
	v_permlane32_swap_b32_e32 v11, v149
	v_pk_mul_f32 v[146:147], v[146:147], v[232:233]
	v_pk_mul_f32 v[148:149], v[148:149], v[234:235]
	v_pk_fma_f32 v[8:9], v[8:9], v[228:229], v[146:147]
	v_pk_fma_f32 v[10:11], v[10:11], v[230:231], v[148:149]
	v_pk_mul_f32 v[8:9], v[8:9], s[24:25] op_sel_hi:[1,0]
	v_pk_mul_f32 v[10:11], v[10:11], s[24:25] op_sel_hi:[1,0]
	v_mov_b32_e32 v146, v4
	v_mov_b32_e32 v147, v5
	v_mov_b32_e32 v148, v6
	v_mov_b32_e32 v149, v7
	v_permlane32_swap_b32_e32 v4, v146
	v_permlane32_swap_b32_e32 v5, v147
	v_permlane32_swap_b32_e32 v6, v148
	v_permlane32_swap_b32_e32 v7, v149
	v_pk_mul_f32 v[146:147], v[146:147], v[200:201]
	v_pk_mul_f32 v[148:149], v[148:149], v[202:203]
	v_pk_fma_f32 v[4:5], v[4:5], v[224:225], v[146:147]
	v_pk_fma_f32 v[6:7], v[6:7], v[226:227], v[148:149]
	v_pk_mul_f32 v[4:5], v[4:5], s[24:25] op_sel_hi:[1,0]
	v_pk_mul_f32 v[6:7], v[6:7], s[24:25] op_sel_hi:[1,0]
	v_mov_b32_e32 v146, v0
	v_mov_b32_e32 v147, v1
	v_mov_b32_e32 v148, v2
	v_mov_b32_e32 v149, v3
	v_permlane32_swap_b32_e32 v0, v146
	v_permlane32_swap_b32_e32 v1, v147
	v_permlane32_swap_b32_e32 v2, v148
	v_permlane32_swap_b32_e32 v3, v149
	v_pk_mul_f32 v[146:147], v[146:147], v[232:233]
	v_pk_mul_f32 v[148:149], v[148:149], v[234:235]
	v_pk_fma_f32 v[0:1], v[0:1], v[228:229], v[146:147]
	v_pk_fma_f32 v[2:3], v[2:3], v[230:231], v[148:149]
	v_pk_mul_f32 v[0:1], v[0:1], s[24:25] op_sel_hi:[1,0]
	v_pk_mul_f32 v[2:3], v[2:3], s[24:25] op_sel_hi:[1,0]
	v_add_u32_e32 v151, 0x9a000, v150
	v_cvt_pk_bf16_f32 v12, v12, v13
	v_cvt_pk_bf16_f32 v13, v14, v15
	v_cvt_pk_bf16_f32 v14, v8, v9
	v_cvt_pk_bf16_f32 v15, v10, v11
	global_store_dwordx4 v151, v[12:15], s[48:49]
	v_cvt_pk_bf16_f32 v4, v4, v5
	v_cvt_pk_bf16_f32 v5, v6, v7
	v_cvt_pk_bf16_f32 v6, v0, v1
	v_cvt_pk_bf16_f32 v7, v2, v3
	global_store_dwordx4 v151, v[4:7], s[48:49] offset:256
	s_branch .Lrope_done
; __device__ __forceinline__ unsigned cvt_pk_bf16(float lo, float hi) { f32x2_t v = {lo, hi}; bf16x2_t b = __builtin_convertvector(v, bf16x2_t); return __builtin_bit_cast(unsigned, b); }
;     __device__ __forceinline__ void operator()(const f32x4 (&acc)[2][2][4][2], const Unit& u, int wr, int wc, int fr, int fq) const {
;     ...
;             for (int m = 0; m < 4; ++m) { const int row = row0 + ai * HALF + m * 16; bf16_t* rowp = O + (size_t)row * ldc + col0;
;                 const int s = row % seq; const int pos = axis ? (s & 63) : (s >> 6);
;                 const f32x4* rp = (const f32x4*)(rope + ((size_t)pos * 16 + i0) * 2);
; #pragma unroll
;                 for (int bj = 0; bj < 2; ++bj) { f32x4 v0 = acc[ai][bj][m][0], v1 = acc[ai][bj][m][1];
;                     const bool do_rope = (u.pn < 2) || (u.pn == 2 && bj == 0);
;                     if (do_rope) {
;                         const f32x4 cs0 = rp[0], cs1 = rp[1], cs2 = rp[2], cs3 = rp[3];
;                         f32x4 p0, p1;
; #pragma unroll
;                         for (int j = 0; j < 4; ++j) { p0[j] = __shfl_xor(v0[j], 32); p1[j] = __shfl_xor(v1[j], 32); }
;                         const float sc = (u.pn < 2) ? 0.125f * 1.4426950408889634f : 1.0f;
;                         v0[0] = (v0[0] * cs0[0] + sgn * p0[0] * cs0[1]) * sc; v0[1] = (v0[1] * cs0[2] + sgn * p0[1] * cs0[3]) * sc;
;                         v0[2] = (v0[2] * cs1[0] + sgn * p0[2] * cs1[1]) * sc; v0[3] = (v0[3] * cs1[2] + sgn * p0[3] * cs1[3]) * sc;
;                         v1[0] = (v1[0] * cs2[0] + sgn * p1[0] * cs2[1]) * sc; v1[1] = (v1[1] * cs2[2] + sgn * p1[1] * cs2[3]) * sc;
;                         v1[2] = (v1[2] * cs3[0] + sgn * p1[2] * cs3[1]) * sc; v1[3] = (v1[3] * cs3[2] + sgn * p1[3] * cs3[3]) * sc;
;                     }
;                     u32x4 w; w.x = cvt_pk_bf16(v0[0], v0[1]); w.y = cvt_pk_bf16(v0[2], v0[3]); w.z = cvt_pk_bf16(v1[0], v1[1]); w.w = cvt_pk_bf16(v1[2], v1[3]);
;                     *(u32x4*)(rowp + bj * HALF) = w; } }
.Lrope_k:
	v_and_b32_e32 v236, 8, v162
	v_lshlrev_b32_e32 v236, 3, v236
	s_add_u32 s60, s50, 0x130000
	s_addc_u32 s61, s51, 0
	s_mov_b32 s58, -1
	s_mov_b32 s59, 0
	v_mov_b32_e32 v237, v167
	v_bfe_u32 v151, v237, 6, 8
	v_and_b32_e32 v237, 63, v237
	v_cndmask_b32_e64 v237, v237, v151, s[8:9]
	v_lshl_add_u32 v149, v237, 7, v236
	global_load_dwordx4 v[168:171], v149, s[60:61]
	global_load_dwordx4 v[172:175], v149, s[60:61] offset:16
	global_load_dwordx4 v[176:179], v149, s[60:61] offset:32
	global_load_dwordx4 v[180:183], v149, s[60:61] offset:48
	v_add_u32_e32 v237, 16, v167
	v_bfe_u32 v151, v237, 6, 8
	v_and_b32_e32 v237, 63, v237
	v_cndmask_b32_e64 v237, v237, v151, s[8:9]
	v_lshl_add_u32 v149, v237, 7, v236
	global_load_dwordx4 v[184:187], v149, s[60:61]
	global_load_dwordx4 v[188:191], v149, s[60:61] offset:16
	global_load_dwordx4 v[192:195], v149, s[60:61] offset:32
	global_load_dwordx4 v[196:199], v149, s[60:61] offset:48
	v_add_u32_e32 v237, 32, v167
	v_bfe_u32 v151, v237, 6, 8
	v_and_b32_e32 v237, 63, v237
	v_cndmask_b32_e64 v237, v237, v151, s[8:9]
	v_lshl_add_u32 v149, v237, 7, v236
	global_load_dwordx4 v[208:211], v149, s[60:61]
	global_load_dwordx4 v[212:215], v149, s[60:61] offset:16
	global_load_dwordx4 v[216:219], v149, s[60:61] offset:32
	global_load_dwordx4 v[220:223], v149, s[60:61] offset:48
	s_waitcnt vmcnt(8)
	v_cndmask_b32_e64 v224, v169, v168, s[58:59]
	v_cndmask_b32_e64 v200, v168, -v169, s[58:59]
	v_cndmask_b32_e64 v225, v171, v170, s[58:59]
	v_cndmask_b32_e64 v201, v170, -v171, s[58:59]
	v_cndmask_b32_e64 v226, v173, v172, s[58:59]
	v_cndmask_b32_e64 v202, v172, -v173, s[58:59]
	v_cndmask_b32_e64 v227, v175, v174, s[58:59]
	v_cndmask_b32_e64 v203, v174, -v175, s[58:59]
	v_cndmask_b32_e64 v228, v177, v176, s[58:59]
	v_cndmask_b32_e64 v232, v176, -v177, s[58:59]
	v_cndmask_b32_e64 v229, v179, v178, s[58:59]
	v_cndmask_b32_e64 v233, v178, -v179, s[58:59]
	v_cndmask_b32_e64 v230, v181, v180, s[58:59]
	v_cndmask_b32_e64 v234, v180, -v181, s[58:59]
	v_cndmask_b32_e64 v231, v183, v182, s[58:59]
	v_cndmask_b32_e64 v235, v182, -v183, s[58:59]
	v_add_u32_e32 v237, 48, v167
	v_bfe_u32 v151, v237, 6, 8
	v_and_b32_e32 v237, 63, v237
	v_cndmask_b32_e64 v237, v237, v151, s[8:9]
	v_lshl_add_u32 v149, v237, 7, v236
	global_load_dwordx4 v[168:171], v149, s[60:61]
	global_load_dwordx4 v[172:175], v149, s[60:61] offset:16
	global_load_dwordx4 v[176:179], v149, s[60:61] offset:32
	global_load_dwordx4 v[180:183], v149, s[60:61] offset:48
	v_mov_b32_e32 v146, v124
	v_mov_b32_e32 v147, v125
	v_mov_b32_e32 v148, v126
	v_mov_b32_e32 v149, v127
	v_permlane32_swap_b32_e32 v124, v146
	v_permlane32_swap_b32_e32 v125, v147
	v_permlane32_swap_b32_e32 v126, v148
	v_permlane32_swap_b32_e32 v127, v149
	v_pk_mul_f32 v[146:147], v[146:147], v[200:201]
	v_pk_mul_f32 v[148:149], v[148:149], v[202:203]
	v_pk_fma_f32 v[124:125], v[124:125], v[224:225], v[146:147]
	v_pk_fma_f32 v[126:127], v[126:127], v[226:227], v[148:149]
	v_mov_b32_e32 v146, v120
	v_mov_b32_e32 v147, v121
	v_mov_b32_e32 v148, v122
	v_mov_b32_e32 v149, v123
	v_permlane32_swap_b32_e32 v120, v146
	v_permlane32_swap_b32_e32 v121, v147
	v_permlane32_swap_b32_e32 v122, v148
	v_permlane32_swap_b32_e32 v123, v149
	v_pk_mul_f32 v[146:147], v[146:147], v[232:233]
	v_pk_mul_f32 v[148:149], v[148:149], v[234:235]
	v_pk_fma_f32 v[120:121], v[120:121], v[228:229], v[146:147]
	v_pk_fma_f32 v[122:123], v[122:123], v[230:231], v[148:149]
	v_mov_b32_e32 v151, v150
	v_cvt_pk_bf16_f32 v124, v124, v125
	v_cvt_pk_bf16_f32 v125, v126, v127
	v_cvt_pk_bf16_f32 v126, v120, v121
	v_cvt_pk_bf16_f32 v127, v122, v123
	global_store_dwordx4 v151, v[124:127], s[48:49]
	v_cvt_pk_bf16_f32 v116, v116, v117
	v_cvt_pk_bf16_f32 v117, v118, v119
	v_cvt_pk_bf16_f32 v118, v112, v113
	v_cvt_pk_bf16_f32 v119, v114, v115
	global_store_dwordx4 v151, v[116:119], s[48:49] offset:256
	s_waitcnt vmcnt(10)
	v_cndmask_b32_e64 v224, v185, v184, s[58:59]
	v_cndmask_b32_e64 v200, v184, -v185, s[58:59]
	v_cndmask_b32_e64 v225, v187, v186, s[58:59]
	v_cndmask_b32_e64 v201, v186, -v187, s[58:59]
	v_cndmask_b32_e64 v226, v189, v188, s[58:59]
	v_cndmask_b32_e64 v202, v188, -v189, s[58:59]
	v_cndmask_b32_e64 v227, v191, v190, s[58:59]
	v_cndmask_b32_e64 v203, v190, -v191, s[58:59]
	v_cndmask_b32_e64 v228, v193, v192, s[58:59]
	v_cndmask_b32_e64 v232, v192, -v193, s[58:59]
	v_cndmask_b32_e64 v229, v195, v194, s[58:59]
	v_cndmask_b32_e64 v233, v194, -v195, s[58:59]
	v_cndmask_b32_e64 v230, v197, v196, s[58:59]
	v_cndmask_b32_e64 v234, v196, -v197, s[58:59]
	v_cndmask_b32_e64 v231, v199, v198, s[58:59]
	v_cndmask_b32_e64 v235, v198, -v199, s[58:59]
	v_add_u32_e32 v237, 128, v167
	v_bfe_u32 v151, v237, 6, 8
	v_and_b32_e32 v237, 63, v237
	v_cndmask_b32_e64 v237, v237, v151, s[8:9]
	v_lshl_add_u32 v149, v237, 7, v236
	global_load_dwordx4 v[184:187], v149, s[60:61]
	global_load_dwordx4 v[188:191], v149, s[60:61] offset:16
	global_load_dwordx4 v[192:195], v149, s[60:61] offset:32
	global_load_dwordx4 v[196:199], v149, s[60:61] offset:48
	v_mov_b32_e32 v146, v108
	v_mov_b32_e32 v147, v109
	v_mov_b32_e32 v148, v110
	v_mov_b32_e32 v149, v111
	v_permlane32_swap_b32_e32 v108, v146
	v_permlane32_swap_b32_e32 v109, v147
	v_permlane32_swap_b32_e32 v110, v148
	v_permlane32_swap_b32_e32 v111, v149
	v_pk_mul_f32 v[146:147], v[146:147], v[200:201]
	v_pk_mul_f32 v[148:149], v[148:149], v[202:203]
	v_pk_fma_f32 v[108:109], v[108:109], v[224:225], v[146:147]
	v_pk_fma_f32 v[110:111], v[110:111], v[226:227], v[148:149]
	v_mov_b32_e32 v146, v104
	v_mov_b32_e32 v147, v105
	v_mov_b32_e32 v148, v106
	v_mov_b32_e32 v149, v107
	v_permlane32_swap_b32_e32 v104, v146
	v_permlane32_swap_b32_e32 v105, v147
	v_permlane32_swap_b32_e32 v106, v148
	v_permlane32_swap_b32_e32 v107, v149
	v_pk_mul_f32 v[146:147], v[146:147], v[232:233]
	v_pk_mul_f32 v[148:149], v[148:149], v[234:235]
	v_pk_fma_f32 v[104:105], v[104:105], v[228:229], v[146:147]
	v_pk_fma_f32 v[106:107], v[106:107], v[230:231], v[148:149]
	v_add_u32_e32 v151, 0xe000, v150
	v_cvt_pk_bf16_f32 v108, v108, v109
	v_cvt_pk_bf16_f32 v109, v110, v111
	v_cvt_pk_bf16_f32 v110, v104, v105
	v_cvt_pk_bf16_f32 v111, v106, v107
	global_store_dwordx4 v151, v[108:111], s[48:49]
	v_cvt_pk_bf16_f32 v100, v100, v101
	v_cvt_pk_bf16_f32 v101, v102, v103
	v_cvt_pk_bf16_f32 v102, v96, v97
	v_cvt_pk_bf16_f32 v103, v98, v99
	global_store_dwordx4 v151, v[100:103], s[48:49] offset:256
	s_waitcnt vmcnt(12)
; __device__ __forceinline__ unsigned cvt_pk_bf16(float lo, float hi) { f32x2_t v = {lo, hi}; bf16x2_t b = __builtin_convertvector(v, bf16x2_t); return __builtin_bit_cast(unsigned, b); }
;     __device__ __forceinline__ void operator()(const f32x4 (&acc)[2][2][4][2], const Unit& u, int wr, int wc, int fr, int fq) const {
;     ...
;             for (int m = 0; m < 4; ++m) { const int row = row0 + ai * HALF + m * 16; bf16_t* rowp = O + (size_t)row * ldc + col0;
;                 const int s = row % seq; const int pos = axis ? (s & 63) : (s >> 6);
;                 const f32x4* rp = (const f32x4*)(rope + ((size_t)pos * 16 + i0) * 2);
; #pragma unroll
;                 for (int bj = 0; bj < 2; ++bj) { f32x4 v0 = acc[ai][bj][m][0], v1 = acc[ai][bj][m][1];
;                     const bool do_rope = (u.pn < 2) || (u.pn == 2 && bj == 0);
;                     if (do_rope) {
;                         const f32x4 cs0 = rp[0], cs1 = rp[1], cs2 = rp[2], cs3 = rp[3];
;                         f32x4 p0, p1;
; #pragma unroll
;                         for (int j = 0; j < 4; ++j) { p0[j] = __shfl_xor(v0[j], 32); p1[j] = __shfl_xor(v1[j], 32); }
;                         const float sc = (u.pn < 2) ? 0.125f * 1.4426950408889634f : 1.0f;
;                         v0[0] = (v0[0] * cs0[0] + sgn * p0[0] * cs0[1]) * sc; v0[1] = (v0[1] * cs0[2] + sgn * p0[1] * cs0[3]) * sc;
;                         v0[2] = (v0[2] * cs1[0] + sgn * p0[2] * cs1[1]) * sc; v0[3] = (v0[3] * cs1[2] + sgn * p0[3] * cs1[3]) * sc;
;                         v1[0] = (v1[0] * cs2[0] + sgn * p1[0] * cs2[1]) * sc; v1[1] = (v1[1] * cs2[2] + sgn * p1[1] * cs2[3]) * sc;
;                         v1[2] = (v1[2] * cs3[0] + sgn * p1[2] * cs3[1]) * sc; v1[3] = (v1[3] * cs3[2] + sgn * p1[3] * cs3[3]) * sc;
;                     }
;                     u32x4 w; w.x = cvt_pk_bf16(v0[0], v0[1]); w.y = cvt_pk_bf16(v0[2], v0[3]); w.z = cvt_pk_bf16(v1[0], v1[1]); w.w = cvt_pk_bf16(v1[2], v1[3]);
;                     *(u32x4*)(rowp + bj * HALF) = w; } }
	v_cndmask_b32_e64 v224, v209, v208, s[58:59]
	v_cndmask_b32_e64 v200, v208, -v209, s[58:59]
	v_cndmask_b32_e64 v225, v211, v210, s[58:59]
	v_cndmask_b32_e64 v201, v210, -v211, s[58:59]
	v_cndmask_b32_e64 v226, v213, v212, s[58:59]
	v_cndmask_b32_e64 v202, v212, -v213, s[58:59]
	v_cndmask_b32_e64 v227, v215, v214, s[58:59]
	v_cndmask_b32_e64 v203, v214, -v215, s[58:59]
	v_cndmask_b32_e64 v228, v217, v216, s[58:59]
	v_cndmask_b32_e64 v232, v216, -v217, s[58:59]
	v_cndmask_b32_e64 v229, v219, v218, s[58:59]
	v_cndmask_b32_e64 v233, v218, -v219, s[58:59]
	v_cndmask_b32_e64 v230, v221, v220, s[58:59]
	v_cndmask_b32_e64 v234, v220, -v221, s[58:59]
	v_cndmask_b32_e64 v231, v223, v222, s[58:59]
	v_cndmask_b32_e64 v235, v222, -v223, s[58:59]
	v_add_u32_e32 v237, 144, v167
	v_bfe_u32 v151, v237, 6, 8
	v_and_b32_e32 v237, 63, v237
	v_cndmask_b32_e64 v237, v237, v151, s[8:9]
	v_lshl_add_u32 v149, v237, 7, v236
	global_load_dwordx4 v[208:211], v149, s[60:61]
	global_load_dwordx4 v[212:215], v149, s[60:61] offset:16
	global_load_dwordx4 v[216:219], v149, s[60:61] offset:32
	global_load_dwordx4 v[220:223], v149, s[60:61] offset:48
	v_mov_b32_e32 v146, v92
	v_mov_b32_e32 v147, v93
	v_mov_b32_e32 v148, v94
	v_mov_b32_e32 v149, v95
	v_permlane32_swap_b32_e32 v92, v146
	v_permlane32_swap_b32_e32 v93, v147
	v_permlane32_swap_b32_e32 v94, v148
	v_permlane32_swap_b32_e32 v95, v149
	v_pk_mul_f32 v[146:147], v[146:147], v[200:201]
	v_pk_mul_f32 v[148:149], v[148:149], v[202:203]
	v_pk_fma_f32 v[92:93], v[92:93], v[224:225], v[146:147]
	v_pk_fma_f32 v[94:95], v[94:95], v[226:227], v[148:149]
	v_mov_b32_e32 v146, v88
	v_mov_b32_e32 v147, v89
	v_mov_b32_e32 v148, v90
	v_mov_b32_e32 v149, v91
	v_permlane32_swap_b32_e32 v88, v146
	v_permlane32_swap_b32_e32 v89, v147
	v_permlane32_swap_b32_e32 v90, v148
	v_permlane32_swap_b32_e32 v91, v149
	v_pk_mul_f32 v[146:147], v[146:147], v[232:233]
	v_pk_mul_f32 v[148:149], v[148:149], v[234:235]
	v_pk_fma_f32 v[88:89], v[88:89], v[228:229], v[146:147]
	v_pk_fma_f32 v[90:91], v[90:91], v[230:231], v[148:149]
	v_add_u32_e32 v151, 0x1c000, v150
	v_cvt_pk_bf16_f32 v92, v92, v93
	v_cvt_pk_bf16_f32 v93, v94, v95
	v_cvt_pk_bf16_f32 v94, v88, v89
	v_cvt_pk_bf16_f32 v95, v90, v91
	global_store_dwordx4 v151, v[92:95], s[48:49]
	v_cvt_pk_bf16_f32 v84, v84, v85
	v_cvt_pk_bf16_f32 v85, v86, v87
	v_cvt_pk_bf16_f32 v86, v80, v81
	v_cvt_pk_bf16_f32 v87, v82, v83
	global_store_dwordx4 v151, v[84:87], s[48:49] offset:256
	s_waitcnt vmcnt(14)
	v_cndmask_b32_e64 v224, v169, v168, s[58:59]
	v_cndmask_b32_e64 v200, v168, -v169, s[58:59]
	v_cndmask_b32_e64 v225, v171, v170, s[58:59]
	v_cndmask_b32_e64 v201, v170, -v171, s[58:59]
	v_cndmask_b32_e64 v226, v173, v172, s[58:59]
	v_cndmask_b32_e64 v202, v172, -v173, s[58:59]
	v_cndmask_b32_e64 v227, v175, v174, s[58:59]
	v_cndmask_b32_e64 v203, v174, -v175, s[58:59]
	v_cndmask_b32_e64 v228, v177, v176, s[58:59]
	v_cndmask_b32_e64 v232, v176, -v177, s[58:59]
	v_cndmask_b32_e64 v229, v179, v178, s[58:59]
	v_cndmask_b32_e64 v233, v178, -v179, s[58:59]
	v_cndmask_b32_e64 v230, v181, v180, s[58:59]
	v_cndmask_b32_e64 v234, v180, -v181, s[58:59]
	v_cndmask_b32_e64 v231, v183, v182, s[58:59]
	v_cndmask_b32_e64 v235, v182, -v183, s[58:59]
	v_add_u32_e32 v237, 160, v167
	v_bfe_u32 v151, v237, 6, 8
	v_and_b32_e32 v237, 63, v237
	v_cndmask_b32_e64 v237, v237, v151, s[8:9]
	v_lshl_add_u32 v149, v237, 7, v236
	global_load_dwordx4 v[168:171], v149, s[60:61]
	global_load_dwordx4 v[172:175], v149, s[60:61] offset:16
	global_load_dwordx4 v[176:179], v149, s[60:61] offset:32
	global_load_dwordx4 v[180:183], v149, s[60:61] offset:48
	v_mov_b32_e32 v146, v76
	v_mov_b32_e32 v147, v77
	v_mov_b32_e32 v148, v78
	v_mov_b32_e32 v149, v79
	v_permlane32_swap_b32_e32 v76, v146
	v_permlane32_swap_b32_e32 v77, v147
	v_permlane32_swap_b32_e32 v78, v148
	v_permlane32_swap_b32_e32 v79, v149
	v_pk_mul_f32 v[146:147], v[146:147], v[200:201]
	v_pk_mul_f32 v[148:149], v[148:149], v[202:203]
	v_pk_fma_f32 v[76:77], v[76:77], v[224:225], v[146:147]
	v_pk_fma_f32 v[78:79], v[78:79], v[226:227], v[148:149]
	v_mov_b32_e32 v146, v72
	v_mov_b32_e32 v147, v73
	v_mov_b32_e32 v148, v74
	v_mov_b32_e32 v149, v75
	v_permlane32_swap_b32_e32 v72, v146
	v_permlane32_swap_b32_e32 v73, v147
	v_permlane32_swap_b32_e32 v74, v148
	v_permlane32_swap_b32_e32 v75, v149
	v_pk_mul_f32 v[146:147], v[146:147], v[232:233]
	v_pk_mul_f32 v[148:149], v[148:149], v[234:235]
	v_pk_fma_f32 v[72:73], v[72:73], v[228:229], v[146:147]
	v_pk_fma_f32 v[74:75], v[74:75], v[230:231], v[148:149]
	v_add_u32_e32 v151, 0x2a000, v150
	v_cvt_pk_bf16_f32 v76, v76, v77
	v_cvt_pk_bf16_f32 v77, v78, v79
	v_cvt_pk_bf16_f32 v78, v72, v73
	v_cvt_pk_bf16_f32 v79, v74, v75
	global_store_dwordx4 v151, v[76:79], s[48:49]
	v_cvt_pk_bf16_f32 v68, v68, v69
	v_cvt_pk_bf16_f32 v69, v70, v71
	v_cvt_pk_bf16_f32 v70, v64, v65
	v_cvt_pk_bf16_f32 v71, v66, v67
	global_store_dwordx4 v151, v[68:71], s[48:49] offset:256
	s_waitcnt vmcnt(14)
; __device__ __forceinline__ unsigned cvt_pk_bf16(float lo, float hi) { f32x2_t v = {lo, hi}; bf16x2_t b = __builtin_convertvector(v, bf16x2_t); return __builtin_bit_cast(unsigned, b); }
;     __device__ __forceinline__ void operator()(const f32x4 (&acc)[2][2][4][2], const Unit& u, int wr, int wc, int fr, int fq) const {
;     ...
;             for (int m = 0; m < 4; ++m) { const int row = row0 + ai * HALF + m * 16; bf16_t* rowp = O + (size_t)row * ldc + col0;
;                 const int s = row % seq; const int pos = axis ? (s & 63) : (s >> 6);
;                 const f32x4* rp = (const f32x4*)(rope + ((size_t)pos * 16 + i0) * 2);
; #pragma unroll
;                 for (int bj = 0; bj < 2; ++bj) { f32x4 v0 = acc[ai][bj][m][0], v1 = acc[ai][bj][m][1];
;                     const bool do_rope = (u.pn < 2) || (u.pn == 2 && bj == 0);
;                     if (do_rope) {
;                         const f32x4 cs0 = rp[0], cs1 = rp[1], cs2 = rp[2], cs3 = rp[3];
;                         f32x4 p0, p1;
; #pragma unroll
;                         for (int j = 0; j < 4; ++j) { p0[j] = __shfl_xor(v0[j], 32); p1[j] = __shfl_xor(v1[j], 32); }
;                         const float sc = (u.pn < 2) ? 0.125f * 1.4426950408889634f : 1.0f;
;                         v0[0] = (v0[0] * cs0[0] + sgn * p0[0] * cs0[1]) * sc; v0[1] = (v0[1] * cs0[2] + sgn * p0[1] * cs0[3]) * sc;
;                         v0[2] = (v0[2] * cs1[0] + sgn * p0[2] * cs1[1]) * sc; v0[3] = (v0[3] * cs1[2] + sgn * p0[3] * cs1[3]) * sc;
;                         v1[0] = (v1[0] * cs2[0] + sgn * p1[0] * cs2[1]) * sc; v1[1] = (v1[1] * cs2[2] + sgn * p1[1] * cs2[3]) * sc;
;                         v1[2] = (v1[2] * cs3[0] + sgn * p1[2] * cs3[1]) * sc; v1[3] = (v1[3] * cs3[2] + sgn * p1[3] * cs3[3]) * sc;
;                     }
;                     u32x4 w; w.x = cvt_pk_bf16(v0[0], v0[1]); w.y = cvt_pk_bf16(v0[2], v0[3]); w.z = cvt_pk_bf16(v1[0], v1[1]); w.w = cvt_pk_bf16(v1[2], v1[3]);
;                     *(u32x4*)(rowp + bj * HALF) = w; } }
	v_cndmask_b32_e64 v224, v185, v184, s[58:59]
	v_cndmask_b32_e64 v200, v184, -v185, s[58:59]
	v_cndmask_b32_e64 v225, v187, v186, s[58:59]
	v_cndmask_b32_e64 v201, v186, -v187, s[58:59]
	v_cndmask_b32_e64 v226, v189, v188, s[58:59]
	v_cndmask_b32_e64 v202, v188, -v189, s[58:59]
	v_cndmask_b32_e64 v227, v191, v190, s[58:59]
	v_cndmask_b32_e64 v203, v190, -v191, s[58:59]
	v_cndmask_b32_e64 v228, v193, v192, s[58:59]
	v_cndmask_b32_e64 v232, v192, -v193, s[58:59]
	v_cndmask_b32_e64 v229, v195, v194, s[58:59]
	v_cndmask_b32_e64 v233, v194, -v195, s[58:59]
	v_cndmask_b32_e64 v230, v197, v196, s[58:59]
	v_cndmask_b32_e64 v234, v196, -v197, s[58:59]
	v_cndmask_b32_e64 v231, v199, v198, s[58:59]
	v_cndmask_b32_e64 v235, v198, -v199, s[58:59]
	v_add_u32_e32 v237, 176, v167
	v_bfe_u32 v151, v237, 6, 8
	v_and_b32_e32 v237, 63, v237
	v_cndmask_b32_e64 v237, v237, v151, s[8:9]
	v_lshl_add_u32 v149, v237, 7, v236
	global_load_dwordx4 v[184:187], v149, s[60:61]
	global_load_dwordx4 v[188:191], v149, s[60:61] offset:16
	global_load_dwordx4 v[192:195], v149, s[60:61] offset:32
	global_load_dwordx4 v[196:199], v149, s[60:61] offset:48
	v_mov_b32_e32 v146, v60
	v_mov_b32_e32 v147, v61
	v_mov_b32_e32 v148, v62
	v_mov_b32_e32 v149, v63
	v_permlane32_swap_b32_e32 v60, v146
	v_permlane32_swap_b32_e32 v61, v147
	v_permlane32_swap_b32_e32 v62, v148
	v_permlane32_swap_b32_e32 v63, v149
	v_pk_mul_f32 v[146:147], v[146:147], v[200:201]
	v_pk_mul_f32 v[148:149], v[148:149], v[202:203]
	v_pk_fma_f32 v[60:61], v[60:61], v[224:225], v[146:147]
	v_pk_fma_f32 v[62:63], v[62:63], v[226:227], v[148:149]
	v_mov_b32_e32 v146, v56
	v_mov_b32_e32 v147, v57
	v_mov_b32_e32 v148, v58
	v_mov_b32_e32 v149, v59
	v_permlane32_swap_b32_e32 v56, v146
	v_permlane32_swap_b32_e32 v57, v147
	v_permlane32_swap_b32_e32 v58, v148
	v_permlane32_swap_b32_e32 v59, v149
	v_pk_mul_f32 v[146:147], v[146:147], v[232:233]
	v_pk_mul_f32 v[148:149], v[148:149], v[234:235]
	v_pk_fma_f32 v[56:57], v[56:57], v[228:229], v[146:147]
	v_pk_fma_f32 v[58:59], v[58:59], v[230:231], v[148:149]
	v_add_u32_e32 v151, 0x70000, v150
	v_cvt_pk_bf16_f32 v60, v60, v61
	v_cvt_pk_bf16_f32 v61, v62, v63
	v_cvt_pk_bf16_f32 v62, v56, v57
	v_cvt_pk_bf16_f32 v63, v58, v59
	global_store_dwordx4 v151, v[60:63], s[48:49]
	v_cvt_pk_bf16_f32 v52, v52, v53
	v_cvt_pk_bf16_f32 v53, v54, v55
	v_cvt_pk_bf16_f32 v54, v48, v49
	v_cvt_pk_bf16_f32 v55, v50, v51
	global_store_dwordx4 v151, v[52:55], s[48:49] offset:256
	s_waitcnt vmcnt(14)
	v_cndmask_b32_e64 v224, v209, v208, s[58:59]
	v_cndmask_b32_e64 v200, v208, -v209, s[58:59]
	v_cndmask_b32_e64 v225, v211, v210, s[58:59]
	v_cndmask_b32_e64 v201, v210, -v211, s[58:59]
	v_cndmask_b32_e64 v226, v213, v212, s[58:59]
	v_cndmask_b32_e64 v202, v212, -v213, s[58:59]
	v_cndmask_b32_e64 v227, v215, v214, s[58:59]
	v_cndmask_b32_e64 v203, v214, -v215, s[58:59]
	v_cndmask_b32_e64 v228, v217, v216, s[58:59]
	v_cndmask_b32_e64 v232, v216, -v217, s[58:59]
	v_cndmask_b32_e64 v229, v219, v218, s[58:59]
	v_cndmask_b32_e64 v233, v218, -v219, s[58:59]
	v_cndmask_b32_e64 v230, v221, v220, s[58:59]
	v_cndmask_b32_e64 v234, v220, -v221, s[58:59]
	v_cndmask_b32_e64 v231, v223, v222, s[58:59]
	v_cndmask_b32_e64 v235, v222, -v223, s[58:59]
	v_mov_b32_e32 v146, v44
	v_mov_b32_e32 v147, v45
	v_mov_b32_e32 v148, v46
	v_mov_b32_e32 v149, v47
	v_permlane32_swap_b32_e32 v44, v146
	v_permlane32_swap_b32_e32 v45, v147
	v_permlane32_swap_b32_e32 v46, v148
	v_permlane32_swap_b32_e32 v47, v149
	v_pk_mul_f32 v[146:147], v[146:147], v[200:201]
	v_pk_mul_f32 v[148:149], v[148:149], v[202:203]
	v_pk_fma_f32 v[44:45], v[44:45], v[224:225], v[146:147]
	v_pk_fma_f32 v[46:47], v[46:47], v[226:227], v[148:149]
	v_mov_b32_e32 v146, v40
	v_mov_b32_e32 v147, v41
	v_mov_b32_e32 v148, v42
	v_mov_b32_e32 v149, v43
	v_permlane32_swap_b32_e32 v40, v146
	v_permlane32_swap_b32_e32 v41, v147
	v_permlane32_swap_b32_e32 v42, v148
	v_permlane32_swap_b32_e32 v43, v149
	v_pk_mul_f32 v[146:147], v[146:147], v[232:233]
	v_pk_mul_f32 v[148:149], v[148:149], v[234:235]
	v_pk_fma_f32 v[40:41], v[40:41], v[228:229], v[146:147]
	v_pk_fma_f32 v[42:43], v[42:43], v[230:231], v[148:149]
	v_add_u32_e32 v151, 0x7e000, v150
	v_cvt_pk_bf16_f32 v44, v44, v45
	v_cvt_pk_bf16_f32 v45, v46, v47
	v_cvt_pk_bf16_f32 v46, v40, v41
	v_cvt_pk_bf16_f32 v47, v42, v43
	global_store_dwordx4 v151, v[44:47], s[48:49]
	v_cvt_pk_bf16_f32 v36, v36, v37
	v_cvt_pk_bf16_f32 v37, v38, v39
	v_cvt_pk_bf16_f32 v38, v32, v33
	v_cvt_pk_bf16_f32 v39, v34, v35
	global_store_dwordx4 v151, v[36:39], s[48:49] offset:256
	s_waitcnt vmcnt(10)
; __device__ __forceinline__ unsigned cvt_pk_bf16(float lo, float hi) { f32x2_t v = {lo, hi}; bf16x2_t b = __builtin_convertvector(v, bf16x2_t); return __builtin_bit_cast(unsigned, b); }
;     __device__ __forceinline__ void operator()(const f32x4 (&acc)[2][2][4][2], const Unit& u, int wr, int wc, int fr, int fq) const {
;     ...
;             for (int m = 0; m < 4; ++m) { const int row = row0 + ai * HALF + m * 16; bf16_t* rowp = O + (size_t)row * ldc + col0;
;                 const int s = row % seq; const int pos = axis ? (s & 63) : (s >> 6);
;                 const f32x4* rp = (const f32x4*)(rope + ((size_t)pos * 16 + i0) * 2);
; #pragma unroll
;                 for (int bj = 0; bj < 2; ++bj) { f32x4 v0 = acc[ai][bj][m][0], v1 = acc[ai][bj][m][1];
;                     const bool do_rope = (u.pn < 2) || (u.pn == 2 && bj == 0);
;                     if (do_rope) {
;                         const f32x4 cs0 = rp[0], cs1 = rp[1], cs2 = rp[2], cs3 = rp[3];
;                         f32x4 p0, p1;
; #pragma unroll
;                         for (int j = 0; j < 4; ++j) { p0[j] = __shfl_xor(v0[j], 32); p1[j] = __shfl_xor(v1[j], 32); }
;                         const float sc = (u.pn < 2) ? 0.125f * 1.4426950408889634f : 1.0f;
;                         v0[0] = (v0[0] * cs0[0] + sgn * p0[0] * cs0[1]) * sc; v0[1] = (v0[1] * cs0[2] + sgn * p0[1] * cs0[3]) * sc;
;                         v0[2] = (v0[2] * cs1[0] + sgn * p0[2] * cs1[1]) * sc; v0[3] = (v0[3] * cs1[2] + sgn * p0[3] * cs1[3]) * sc;
;                         v1[0] = (v1[0] * cs2[0] + sgn * p1[0] * cs2[1]) * sc; v1[1] = (v1[1] * cs2[2] + sgn * p1[1] * cs2[3]) * sc;
;                         v1[2] = (v1[2] * cs3[0] + sgn * p1[2] * cs3[1]) * sc; v1[3] = (v1[3] * cs3[2] + sgn * p1[3] * cs3[3]) * sc;
;                     }
;                     u32x4 w; w.x = cvt_pk_bf16(v0[0], v0[1]); w.y = cvt_pk_bf16(v0[2], v0[3]); w.z = cvt_pk_bf16(v1[0], v1[1]); w.w = cvt_pk_bf16(v1[2], v1[3]);
;                     *(u32x4*)(rowp + bj * HALF) = w; } }
	v_cndmask_b32_e64 v224, v169, v168, s[58:59]
	v_cndmask_b32_e64 v200, v168, -v169, s[58:59]
	v_cndmask_b32_e64 v225, v171, v170, s[58:59]
	v_cndmask_b32_e64 v201, v170, -v171, s[58:59]
	v_cndmask_b32_e64 v226, v173, v172, s[58:59]
	v_cndmask_b32_e64 v202, v172, -v173, s[58:59]
	v_cndmask_b32_e64 v227, v175, v174, s[58:59]
	v_cndmask_b32_e64 v203, v174, -v175, s[58:59]
	v_cndmask_b32_e64 v228, v177, v176, s[58:59]
	v_cndmask_b32_e64 v232, v176, -v177, s[58:59]
	v_cndmask_b32_e64 v229, v179, v178, s[58:59]
	v_cndmask_b32_e64 v233, v178, -v179, s[58:59]
	v_cndmask_b32_e64 v230, v181, v180, s[58:59]
	v_cndmask_b32_e64 v234, v180, -v181, s[58:59]
	v_cndmask_b32_e64 v231, v183, v182, s[58:59]
	v_cndmask_b32_e64 v235, v182, -v183, s[58:59]
	v_mov_b32_e32 v146, v28
	v_mov_b32_e32 v147, v29
	v_mov_b32_e32 v148, v30
	v_mov_b32_e32 v149, v31
	v_permlane32_swap_b32_e32 v28, v146
	v_permlane32_swap_b32_e32 v29, v147
	v_permlane32_swap_b32_e32 v30, v148
	v_permlane32_swap_b32_e32 v31, v149
	v_pk_mul_f32 v[146:147], v[146:147], v[200:201]
	v_pk_mul_f32 v[148:149], v[148:149], v[202:203]
	v_pk_fma_f32 v[28:29], v[28:29], v[224:225], v[146:147]
	v_pk_fma_f32 v[30:31], v[30:31], v[226:227], v[148:149]
	v_mov_b32_e32 v146, v24
	v_mov_b32_e32 v147, v25
	v_mov_b32_e32 v148, v26
	v_mov_b32_e32 v149, v27
	v_permlane32_swap_b32_e32 v24, v146
	v_permlane32_swap_b32_e32 v25, v147
	v_permlane32_swap_b32_e32 v26, v148
	v_permlane32_swap_b32_e32 v27, v149
	v_pk_mul_f32 v[146:147], v[146:147], v[232:233]
	v_pk_mul_f32 v[148:149], v[148:149], v[234:235]
	v_pk_fma_f32 v[24:25], v[24:25], v[228:229], v[146:147]
	v_pk_fma_f32 v[26:27], v[26:27], v[230:231], v[148:149]
	v_add_u32_e32 v151, 0x8c000, v150
	v_cvt_pk_bf16_f32 v28, v28, v29
	v_cvt_pk_bf16_f32 v29, v30, v31
	v_cvt_pk_bf16_f32 v30, v24, v25
	v_cvt_pk_bf16_f32 v31, v26, v27
	global_store_dwordx4 v151, v[28:31], s[48:49]
	v_cvt_pk_bf16_f32 v20, v20, v21
	v_cvt_pk_bf16_f32 v21, v22, v23
	v_cvt_pk_bf16_f32 v22, v16, v17
	v_cvt_pk_bf16_f32 v23, v18, v19
	global_store_dwordx4 v151, v[20:23], s[48:49] offset:256
	s_waitcnt vmcnt(6)
	v_cndmask_b32_e64 v224, v185, v184, s[58:59]
	v_cndmask_b32_e64 v200, v184, -v185, s[58:59]
	v_cndmask_b32_e64 v225, v187, v186, s[58:59]
	v_cndmask_b32_e64 v201, v186, -v187, s[58:59]
	v_cndmask_b32_e64 v226, v189, v188, s[58:59]
	v_cndmask_b32_e64 v202, v188, -v189, s[58:59]
	v_cndmask_b32_e64 v227, v191, v190, s[58:59]
	v_cndmask_b32_e64 v203, v190, -v191, s[58:59]
	v_cndmask_b32_e64 v228, v193, v192, s[58:59]
	v_cndmask_b32_e64 v232, v192, -v193, s[58:59]
	v_cndmask_b32_e64 v229, v195, v194, s[58:59]
	v_cndmask_b32_e64 v233, v194, -v195, s[58:59]
	v_cndmask_b32_e64 v230, v197, v196, s[58:59]
	v_cndmask_b32_e64 v234, v196, -v197, s[58:59]
	v_cndmask_b32_e64 v231, v199, v198, s[58:59]
	v_cndmask_b32_e64 v235, v198, -v199, s[58:59]
	v_mov_b32_e32 v146, v12
	v_mov_b32_e32 v147, v13
	v_mov_b32_e32 v148, v14
	v_mov_b32_e32 v149, v15
	v_permlane32_swap_b32_e32 v12, v146
	v_permlane32_swap_b32_e32 v13, v147
	v_permlane32_swap_b32_e32 v14, v148
	v_permlane32_swap_b32_e32 v15, v149
	v_pk_mul_f32 v[146:147], v[146:147], v[200:201]
	v_pk_mul_f32 v[148:149], v[148:149], v[202:203]
	v_pk_fma_f32 v[12:13], v[12:13], v[224:225], v[146:147]
	v_pk_fma_f32 v[14:15], v[14:15], v[226:227], v[148:149]
	v_mov_b32_e32 v146, v8
	v_mov_b32_e32 v147, v9
	v_mov_b32_e32 v148, v10
	v_mov_b32_e32 v149, v11
	v_permlane32_swap_b32_e32 v8, v146
	v_permlane32_swap_b32_e32 v9, v147
	v_permlane32_swap_b32_e32 v10, v148
	v_permlane32_swap_b32_e32 v11, v149
	v_pk_mul_f32 v[146:147], v[146:147], v[232:233]
	v_pk_mul_f32 v[148:149], v[148:149], v[234:235]
	v_pk_fma_f32 v[8:9], v[8:9], v[228:229], v[146:147]
	v_pk_fma_f32 v[10:11], v[10:11], v[230:231], v[148:149]
	v_add_u32_e32 v151, 0x9a000, v150
	v_cvt_pk_bf16_f32 v12, v12, v13
	v_cvt_pk_bf16_f32 v13, v14, v15
	v_cvt_pk_bf16_f32 v14, v8, v9
	v_cvt_pk_bf16_f32 v15, v10, v11
	global_store_dwordx4 v151, v[12:15], s[48:49]
	v_cvt_pk_bf16_f32 v4, v4, v5
	v_cvt_pk_bf16_f32 v5, v6, v7
	v_cvt_pk_bf16_f32 v6, v0, v1
	v_cvt_pk_bf16_f32 v7, v2, v3
	global_store_dwordx4 v151, v[4:7], s[48:49] offset:256
.Lrope_done:
	s_andn2_b64 vcc, exec, s[30:31]
	s_mov_b64 s[4:5], -1
	s_cbranch_vccnz .LBB0_333
	s_andn2_b64 vcc, exec, s[14:15]
	s_cbranch_vccnz .LBB0_332
	s_barrier
	s_branch .LBB0_332
